# all hot loop heads (8 GEMM K-loops, attention k-tile loop, 2 GLA loops) aligned to 64 bytes, on top of packed SwiGLU + gate epilogue
# speedup vs baseline: 1.0034x; 1.0034x over previous
.LBB0_78:
	s_ashr_i32 s17, s16, 31
	s_lshl_b64 s[18:19], s[16:17], 17
	s_add_u32 s18, s1, s18
	v_cmp_lt_i64_e32 vcc, s[10:11], v[166:167]
	s_addc_u32 s19, s30, s19
	s_and_b64 s[20:21], vcc, exec
	s_cselect_b32 s29, s19, s23
	s_cselect_b32 s28, s18, s22
	s_ashr_i32 s15, s14, 31
	s_lshl_b64 s[20:21], s[14:15], 17
	s_add_u32 s20, s31, s20
	s_addc_u32 s21, s34, s21
	s_and_b64 s[26:27], vcc, exec
	s_cselect_b32 s27, s21, s25
	s_cselect_b32 s26, s20, s24
	s_add_i32 s44, 0, 0x10000
	v_add_u32_e32 v196, s44, v3
	ds_read_b128 v[6:9], v196
	ds_read_b128 v[10:13], v196 offset:1024
	ds_read_b128 v[14:17], v196 offset:2048
	ds_read_b128 v[18:21], v196 offset:3072
	s_add_u32 s46, s22, 0x10080
	s_addc_u32 s47, s23, 0
	s_add_i32 s45, s13, 0xc000
	v_lshl_add_u64 v[54:55], s[46:47], 0, v[128:129]
	s_mov_b32 m0, s45
	s_add_i32 s15, s13, 0xe000
	ds_read_b128 v[22:25], v5
	ds_read_b128 v[26:29], v5 offset:1024
	ds_read_b128 v[30:33], v5 offset:2048
	ds_read_b128 v[34:37], v5 offset:3072
	ds_read_b128 v[38:41], v5 offset:4096
	ds_read_b128 v[42:45], v5 offset:5120
	ds_read_b128 v[46:49], v5 offset:6144
	ds_read_b128 v[50:53], v5 offset:7168
	global_load_lds_dwordx4 v[54:55], off
	v_lshl_add_u64 v[54:55], s[46:47], 0, v[0:1]
	s_mov_b32 m0, s15
	s_nop 0
	global_load_lds_dwordx4 v[54:55], off
	s_waitcnt lgkmcnt(8)
	s_barrier
	s_waitcnt lgkmcnt(0)
	s_setprio 1
	s_waitcnt lgkmcnt(0)
	v_mfma_f32_16x16x32_bf16 v[54:57], v[6:9], v[22:25], 0
	v_mfma_f32_16x16x32_bf16 v[58:61], v[14:17], v[22:25], 0
	v_mfma_f32_16x16x32_bf16 v[62:65], v[6:9], v[30:33], 0
	v_mfma_f32_16x16x32_bf16 v[66:69], v[14:17], v[30:33], 0
	v_mfma_f32_16x16x32_bf16 v[70:73], v[6:9], v[38:41], 0
	v_mfma_f32_16x16x32_bf16 v[74:77], v[14:17], v[38:41], 0
	v_mfma_f32_16x16x32_bf16 v[78:81], v[6:9], v[46:49], 0
	v_mfma_f32_16x16x32_bf16 v[82:85], v[14:17], v[46:49], 0
	v_mfma_f32_16x16x32_bf16 v[54:57], v[10:13], v[26:29], v[54:57]
	v_mfma_f32_16x16x32_bf16 v[58:61], v[18:21], v[26:29], v[58:61]
	v_mfma_f32_16x16x32_bf16 v[62:65], v[10:13], v[34:37], v[62:65]
	v_mfma_f32_16x16x32_bf16 v[66:69], v[18:21], v[34:37], v[66:69]
	v_mfma_f32_16x16x32_bf16 v[70:73], v[10:13], v[42:45], v[70:73]
	v_mfma_f32_16x16x32_bf16 v[74:77], v[18:21], v[42:45], v[74:77]
	v_mfma_f32_16x16x32_bf16 v[78:81], v[10:13], v[50:53], v[78:81]
	v_mfma_f32_16x16x32_bf16 v[82:85], v[18:21], v[50:53], v[82:85]
	s_setprio 0
	s_barrier
	s_add_i32 s46, 0, 0x14000
	v_lshl_add_u64 v[126:127], s[24:25], 0, v[128:129]
	s_mov_b64 s[48:49], 0x100
	s_add_i32 s44, s44, s35
	v_add_u32_e32 v198, s46, v3
	v_lshl_add_u64 v[102:103], v[126:127], 0, s[48:49]
	s_mov_b32 m0, s44
	v_lshl_add_u64 v[228:229], s[24:25], 0, v[0:1]
	s_add_i32 s17, s44, 0x2000
	ds_read_b128 v[86:89], v198
	ds_read_b128 v[90:93], v198 offset:1024
	ds_read_b128 v[94:97], v198 offset:2048
	ds_read_b128 v[98:101], v198 offset:3072
	global_load_lds_dwordx4 v[102:103], off
	v_lshl_add_u64 v[102:103], v[228:229], 0, s[48:49]
	s_mov_b32 m0, s17
	s_nop 0
	global_load_lds_dwordx4 v[102:103], off
	s_barrier
	s_waitcnt lgkmcnt(0)
	s_setprio 1
	s_waitcnt lgkmcnt(0)
	v_mfma_f32_16x16x32_bf16 v[102:105], v[86:89], v[22:25], 0
	v_mfma_f32_16x16x32_bf16 v[22:25], v[94:97], v[22:25], 0
	v_mfma_f32_16x16x32_bf16 v[102:105], v[90:93], v[26:29], v[102:105]
	v_mfma_f32_16x16x32_bf16 v[22:25], v[98:101], v[26:29], v[22:25]
	v_mfma_f32_16x16x32_bf16 v[26:29], v[86:89], v[30:33], 0
	v_mfma_f32_16x16x32_bf16 v[30:33], v[94:97], v[30:33], 0
	v_mfma_f32_16x16x32_bf16 v[26:29], v[90:93], v[34:37], v[26:29]
	v_mfma_f32_16x16x32_bf16 v[30:33], v[98:101], v[34:37], v[30:33]
	v_mfma_f32_16x16x32_bf16 v[34:37], v[86:89], v[38:41], 0
	v_mfma_f32_16x16x32_bf16 v[38:41], v[94:97], v[38:41], 0
	v_mfma_f32_16x16x32_bf16 v[34:37], v[90:93], v[42:45], v[34:37]
	v_mfma_f32_16x16x32_bf16 v[38:41], v[98:101], v[42:45], v[38:41]
	v_mfma_f32_16x16x32_bf16 v[42:45], v[86:89], v[46:49], 0
	v_mfma_f32_16x16x32_bf16 v[46:49], v[94:97], v[46:49], 0
	v_mfma_f32_16x16x32_bf16 v[42:45], v[90:93], v[50:53], v[42:45]
	v_mfma_f32_16x16x32_bf16 v[46:49], v[98:101], v[50:53], v[46:49]
	s_setprio 0
	v_lshl_add_u64 v[230:231], s[22:23], 0, v[128:129]
	s_mov_b32 m0, s13
	v_lshl_add_u64 v[138:139], v[230:231], 0, s[48:49]
	v_lshl_add_u64 v[232:233], s[22:23], 0, v[0:1]
	s_barrier
	ds_read_b128 v[50:53], v5 offset:16384
	ds_read_b128 v[106:109], v5 offset:17408
	ds_read_b128 v[110:113], v5 offset:18432
	ds_read_b128 v[114:117], v5 offset:19456
	ds_read_b128 v[118:121], v5 offset:20480
	ds_read_b128 v[122:125], v5 offset:21504
	ds_read_b128 v[130:133], v5 offset:22528
	ds_read_b128 v[134:137], v5 offset:23552
	global_load_lds_dwordx4 v[138:139], off
	v_lshl_add_u64 v[138:139], v[232:233], 0, s[48:49]
	s_mov_b32 m0, s36
	s_nop 0
	global_load_lds_dwordx4 v[138:139], off
	s_barrier
	s_waitcnt lgkmcnt(0)
	s_setprio 1
	s_waitcnt lgkmcnt(0)
	v_mfma_f32_16x16x32_bf16 v[138:141], v[6:9], v[50:53], 0
	s_waitcnt vmcnt(0)
	v_mfma_f32_16x16x32_bf16 v[146:149], v[6:9], v[110:113], 0
	v_mfma_f32_16x16x32_bf16 v[154:157], v[6:9], v[118:121], 0
	v_mfma_f32_16x16x32_bf16 v[6:9], v[6:9], v[130:133], 0
	v_mfma_f32_16x16x32_bf16 v[138:141], v[10:13], v[106:109], v[138:141]
	v_mfma_f32_16x16x32_bf16 v[142:145], v[14:17], v[50:53], 0
	v_mfma_f32_16x16x32_bf16 v[146:149], v[10:13], v[114:117], v[146:149]
	v_mfma_f32_16x16x32_bf16 v[150:153], v[14:17], v[110:113], 0
	v_mfma_f32_16x16x32_bf16 v[154:157], v[10:13], v[122:125], v[154:157]
	v_mfma_f32_16x16x32_bf16 v[158:161], v[14:17], v[118:121], 0
	v_mfma_f32_16x16x32_bf16 v[6:9], v[10:13], v[134:137], v[6:9]
	v_mfma_f32_16x16x32_bf16 v[10:13], v[14:17], v[130:133], 0
	v_mfma_f32_16x16x32_bf16 v[142:145], v[18:21], v[106:109], v[142:145]
	v_mfma_f32_16x16x32_bf16 v[150:153], v[18:21], v[114:117], v[150:153]
	v_mfma_f32_16x16x32_bf16 v[158:161], v[18:21], v[122:125], v[158:161]
	v_mfma_f32_16x16x32_bf16 v[10:13], v[18:21], v[134:137], v[10:13]
	s_setprio 0
	s_barrier
	s_add_u32 s48, s24, 0x10100
	s_addc_u32 s49, s25, 0
	s_add_i32 s46, s46, s35
	v_lshl_add_u64 v[14:15], s[48:49], 0, v[128:129]
	s_mov_b32 m0, s46
	s_add_i32 s43, s46, 0x2000
	global_load_lds_dwordx4 v[14:15], off
	v_lshl_add_u64 v[14:15], s[48:49], 0, v[0:1]
	s_mov_b32 m0, s43
	s_nop 0
	global_load_lds_dwordx4 v[14:15], off
	s_waitcnt vmcnt(6)
	s_barrier
	s_setprio 1
	v_mfma_f32_16x16x32_bf16 v[14:17], v[86:89], v[50:53], 0
	v_mfma_f32_16x16x32_bf16 v[18:21], v[94:97], v[50:53], 0
	v_mfma_f32_16x16x32_bf16 v[14:17], v[90:93], v[106:109], v[14:17]
	v_mfma_f32_16x16x32_bf16 v[18:21], v[98:101], v[106:109], v[18:21]
	v_mfma_f32_16x16x32_bf16 v[50:53], v[86:89], v[110:113], 0
	v_mfma_f32_16x16x32_bf16 v[106:109], v[94:97], v[110:113], 0
	v_mfma_f32_16x16x32_bf16 v[110:113], v[86:89], v[118:121], 0
	v_mfma_f32_16x16x32_bf16 v[86:89], v[86:89], v[130:133], 0
	v_mfma_f32_16x16x32_bf16 v[50:53], v[90:93], v[114:117], v[50:53]
	v_mfma_f32_16x16x32_bf16 v[106:109], v[98:101], v[114:117], v[106:109]
	v_mfma_f32_16x16x32_bf16 v[110:113], v[90:93], v[122:125], v[110:113]
	v_mfma_f32_16x16x32_bf16 v[114:117], v[94:97], v[118:121], 0
	v_mfma_f32_16x16x32_bf16 v[86:89], v[90:93], v[134:137], v[86:89]
	v_mfma_f32_16x16x32_bf16 v[90:93], v[94:97], v[130:133], 0
	v_mfma_f32_16x16x32_bf16 v[114:117], v[98:101], v[122:125], v[114:117]
	v_mfma_f32_16x16x32_bf16 v[90:93], v[98:101], v[134:137], v[90:93]
	s_setprio 0
	s_add_i32 s47, 0, 0x18000
	v_add_u32_e32 v200, s47, v3
	s_barrier
	ds_read_b128 v[94:97], v200
	ds_read_b128 v[98:101], v200 offset:1024
	ds_read_b128 v[118:121], v200 offset:2048
	ds_read_b128 v[122:125], v200 offset:3072
	s_add_u32 s48, s22, 0x10100
	s_addc_u32 s49, s23, 0
	s_mov_b32 m0, s37
	v_lshl_add_u64 v[212:213], s[48:49], 0, v[128:129]
	ds_read_b128 v[130:133], v5 offset:32768
	ds_read_b128 v[134:137], v5 offset:33792
	ds_read_b128 v[176:179], v5 offset:34816
	ds_read_b128 v[180:183], v5 offset:35840
	ds_read_b128 v[184:187], v5 offset:36864
	ds_read_b128 v[188:191], v5 offset:37888
	ds_read_b128 v[192:195], v5 offset:38912
	ds_read_b128 v[208:211], v5 offset:39936
	global_load_lds_dwordx4 v[212:213], off
	v_lshl_add_u64 v[212:213], s[48:49], 0, v[0:1]
	s_mov_b32 m0, s38
	s_nop 0
	global_load_lds_dwordx4 v[212:213], off
	s_waitcnt lgkmcnt(8)
	s_barrier
	s_waitcnt lgkmcnt(0)
	s_setprio 1
	s_waitcnt lgkmcnt(0)
	v_mfma_f32_16x16x32_bf16 v[54:57], v[94:97], v[130:133], v[54:57]
	v_mfma_f32_16x16x32_bf16 v[58:61], v[118:121], v[130:133], v[58:61]
	v_mfma_f32_16x16x32_bf16 v[62:65], v[94:97], v[176:179], v[62:65]
	v_mfma_f32_16x16x32_bf16 v[66:69], v[118:121], v[176:179], v[66:69]
	v_mfma_f32_16x16x32_bf16 v[70:73], v[94:97], v[184:187], v[70:73]
	v_mfma_f32_16x16x32_bf16 v[74:77], v[118:121], v[184:187], v[74:77]
	v_mfma_f32_16x16x32_bf16 v[78:81], v[94:97], v[192:195], v[78:81]
	v_mfma_f32_16x16x32_bf16 v[82:85], v[118:121], v[192:195], v[82:85]
	v_mfma_f32_16x16x32_bf16 v[54:57], v[98:101], v[134:137], v[54:57]
	v_mfma_f32_16x16x32_bf16 v[58:61], v[122:125], v[134:137], v[58:61]
	v_mfma_f32_16x16x32_bf16 v[62:65], v[98:101], v[180:183], v[62:65]
	v_mfma_f32_16x16x32_bf16 v[66:69], v[122:125], v[180:183], v[66:69]
	v_mfma_f32_16x16x32_bf16 v[70:73], v[98:101], v[188:191], v[70:73]
	v_mfma_f32_16x16x32_bf16 v[74:77], v[122:125], v[188:191], v[74:77]
	v_mfma_f32_16x16x32_bf16 v[78:81], v[98:101], v[208:211], v[78:81]
	v_mfma_f32_16x16x32_bf16 v[82:85], v[122:125], v[208:211], v[82:85]
	s_setprio 0
	s_barrier
	s_add_i32 s49, 0, 0x1c000
	s_mov_b64 s[50:51], 0x180
	s_add_i32 s48, s47, s35
	v_add_u32_e32 v234, s49, v3
	v_lshl_add_u64 v[126:127], v[126:127], 0, s[50:51]
	s_mov_b32 m0, s48
	s_add_i32 s47, s48, 0x2000
	ds_read_b128 v[212:215], v234
	ds_read_b128 v[216:219], v234 offset:1024
	ds_read_b128 v[220:223], v234 offset:2048
	ds_read_b128 v[224:227], v234 offset:3072
	global_load_lds_dwordx4 v[126:127], off
	v_lshl_add_u64 v[126:127], v[228:229], 0, s[50:51]
	s_mov_b32 m0, s47
	s_nop 0
	global_load_lds_dwordx4 v[126:127], off
	s_barrier
	s_waitcnt lgkmcnt(0)
	s_setprio 1
	s_waitcnt lgkmcnt(0)
	v_mfma_f32_16x16x32_bf16 v[102:105], v[212:215], v[130:133], v[102:105]
	v_mfma_f32_16x16x32_bf16 v[22:25], v[220:223], v[130:133], v[22:25]
	v_mfma_f32_16x16x32_bf16 v[26:29], v[212:215], v[176:179], v[26:29]
	v_mfma_f32_16x16x32_bf16 v[30:33], v[220:223], v[176:179], v[30:33]
	v_mfma_f32_16x16x32_bf16 v[34:37], v[212:215], v[184:187], v[34:37]
	v_mfma_f32_16x16x32_bf16 v[38:41], v[220:223], v[184:187], v[38:41]
	v_mfma_f32_16x16x32_bf16 v[42:45], v[212:215], v[192:195], v[42:45]
	v_mfma_f32_16x16x32_bf16 v[46:49], v[220:223], v[192:195], v[46:49]
	v_mfma_f32_16x16x32_bf16 v[102:105], v[216:219], v[134:137], v[102:105]
	v_mfma_f32_16x16x32_bf16 v[22:25], v[224:227], v[134:137], v[22:25]
	v_mfma_f32_16x16x32_bf16 v[26:29], v[216:219], v[180:183], v[26:29]
	v_mfma_f32_16x16x32_bf16 v[30:33], v[224:227], v[180:183], v[30:33]
	v_mfma_f32_16x16x32_bf16 v[34:37], v[216:219], v[188:191], v[34:37]
	v_mfma_f32_16x16x32_bf16 v[38:41], v[224:227], v[188:191], v[38:41]
	v_mfma_f32_16x16x32_bf16 v[42:45], v[216:219], v[208:211], v[42:45]
	v_mfma_f32_16x16x32_bf16 v[46:49], v[224:227], v[208:211], v[46:49]
	s_setprio 0
	s_mov_b32 m0, s39
	v_lshl_add_u64 v[126:127], v[230:231], 0, s[50:51]
	s_barrier
	ds_read_b128 v[130:133], v5 offset:49152
	ds_read_b128 v[134:137], v5 offset:50176
	ds_read_b128 v[176:179], v5 offset:51200
	ds_read_b128 v[180:183], v5 offset:52224
	ds_read_b128 v[184:187], v5 offset:53248
	ds_read_b128 v[188:191], v5 offset:54272
	ds_read_b128 v[192:195], v5 offset:55296
	ds_read_b128 v[208:211], v5 offset:56320
	global_load_lds_dwordx4 v[126:127], off
	v_lshl_add_u64 v[126:127], v[232:233], 0, s[50:51]
	s_mov_b32 m0, s40
	s_nop 0
	global_load_lds_dwordx4 v[126:127], off
	s_barrier
	s_waitcnt lgkmcnt(0)
	s_setprio 1
	s_waitcnt lgkmcnt(0)
	v_mfma_f32_16x16x32_bf16 v[138:141], v[94:97], v[130:133], v[138:141]
	v_mfma_f32_16x16x32_bf16 v[142:145], v[118:121], v[130:133], v[142:145]
	v_mfma_f32_16x16x32_bf16 v[146:149], v[94:97], v[176:179], v[146:149]
	v_mfma_f32_16x16x32_bf16 v[150:153], v[118:121], v[176:179], v[150:153]
	v_mfma_f32_16x16x32_bf16 v[154:157], v[94:97], v[184:187], v[154:157]
	v_mfma_f32_16x16x32_bf16 v[158:161], v[118:121], v[184:187], v[158:161]
	v_mfma_f32_16x16x32_bf16 v[6:9], v[94:97], v[192:195], v[6:9]
	v_mfma_f32_16x16x32_bf16 v[10:13], v[118:121], v[192:195], v[10:13]
	v_mfma_f32_16x16x32_bf16 v[138:141], v[98:101], v[134:137], v[138:141]
	v_mfma_f32_16x16x32_bf16 v[142:145], v[122:125], v[134:137], v[142:145]
	v_mfma_f32_16x16x32_bf16 v[146:149], v[98:101], v[180:183], v[146:149]
	v_mfma_f32_16x16x32_bf16 v[150:153], v[122:125], v[180:183], v[150:153]
	v_mfma_f32_16x16x32_bf16 v[154:157], v[98:101], v[188:191], v[154:157]
	v_mfma_f32_16x16x32_bf16 v[158:161], v[122:125], v[188:191], v[158:161]
	v_mfma_f32_16x16x32_bf16 v[6:9], v[98:101], v[208:211], v[6:9]
	v_mfma_f32_16x16x32_bf16 v[10:13], v[122:125], v[208:211], v[10:13]
	s_setprio 0
	s_barrier
	s_add_u32 s50, s24, 0x10180
	s_addc_u32 s51, s25, 0
	s_add_i32 s25, s49, s35
	v_lshl_add_u64 v[94:95], s[50:51], 0, v[128:129]
	s_mov_b32 m0, s25
	s_add_i32 s24, s25, 0x2000
	global_load_lds_dwordx4 v[94:95], off
	v_lshl_add_u64 v[94:95], s[50:51], 0, v[0:1]
	s_mov_b32 m0, s24
	s_nop 0
	global_load_lds_dwordx4 v[94:95], off
	s_waitcnt vmcnt(6)
	s_barrier
	s_setprio 1
	v_mfma_f32_16x16x32_bf16 v[14:17], v[212:215], v[130:133], v[14:17]
	v_mfma_f32_16x16x32_bf16 v[18:21], v[220:223], v[130:133], v[18:21]
	v_mfma_f32_16x16x32_bf16 v[50:53], v[212:215], v[176:179], v[50:53]
	v_mfma_f32_16x16x32_bf16 v[94:97], v[220:223], v[176:179], v[106:109]
	v_mfma_f32_16x16x32_bf16 v[98:101], v[212:215], v[184:187], v[110:113]
	v_mfma_f32_16x16x32_bf16 v[106:109], v[220:223], v[184:187], v[114:117]
	v_mfma_f32_16x16x32_bf16 v[86:89], v[212:215], v[192:195], v[86:89]
	v_mfma_f32_16x16x32_bf16 v[90:93], v[220:223], v[192:195], v[90:93]
	v_mfma_f32_16x16x32_bf16 v[14:17], v[216:219], v[134:137], v[14:17]
	v_mfma_f32_16x16x32_bf16 v[18:21], v[224:227], v[134:137], v[18:21]
	v_mfma_f32_16x16x32_bf16 v[50:53], v[216:219], v[180:183], v[50:53]
	v_mfma_f32_16x16x32_bf16 v[94:97], v[224:227], v[180:183], v[94:97]
	v_mfma_f32_16x16x32_bf16 v[98:101], v[216:219], v[188:191], v[98:101]
	v_mfma_f32_16x16x32_bf16 v[106:109], v[224:227], v[188:191], v[106:109]
	v_mfma_f32_16x16x32_bf16 v[86:89], v[216:219], v[208:211], v[86:89]
	v_mfma_f32_16x16x32_bf16 v[90:93], v[224:227], v[208:211], v[90:93]
	s_setprio 0
	s_barrier
	ds_read_b128 v[110:113], v196
	ds_read_b128 v[114:117], v196 offset:1024
	ds_read_b128 v[118:121], v196 offset:2048
	ds_read_b128 v[122:125], v196 offset:3072
	s_add_u32 s22, s22, 0x10180
	s_addc_u32 s23, s23, 0
	s_mov_b32 m0, s45
	v_lshl_add_u64 v[126:127], s[22:23], 0, v[128:129]
	ds_read_b128 v[130:133], v5
	ds_read_b128 v[134:137], v5 offset:1024
	ds_read_b128 v[176:179], v5 offset:2048
	ds_read_b128 v[180:183], v5 offset:3072
	ds_read_b128 v[184:187], v5 offset:4096
	ds_read_b128 v[188:191], v5 offset:5120
	ds_read_b128 v[192:195], v5 offset:6144
	ds_read_b128 v[208:211], v5 offset:7168
	global_load_lds_dwordx4 v[126:127], off
	v_lshl_add_u64 v[126:127], s[22:23], 0, v[0:1]
	s_mov_b32 m0, s15
	s_nop 0
	global_load_lds_dwordx4 v[126:127], off
	s_waitcnt lgkmcnt(8)
	s_barrier
	s_waitcnt lgkmcnt(0)
	s_setprio 1
	s_waitcnt lgkmcnt(0)
	v_mfma_f32_16x16x32_bf16 v[54:57], v[110:113], v[130:133], v[54:57]
	v_mfma_f32_16x16x32_bf16 v[58:61], v[118:121], v[130:133], v[58:61]
	v_mfma_f32_16x16x32_bf16 v[62:65], v[110:113], v[176:179], v[62:65]
	v_mfma_f32_16x16x32_bf16 v[66:69], v[118:121], v[176:179], v[66:69]
	v_mfma_f32_16x16x32_bf16 v[70:73], v[110:113], v[184:187], v[70:73]
	v_mfma_f32_16x16x32_bf16 v[74:77], v[118:121], v[184:187], v[74:77]
	v_mfma_f32_16x16x32_bf16 v[78:81], v[110:113], v[192:195], v[78:81]
	v_mfma_f32_16x16x32_bf16 v[82:85], v[118:121], v[192:195], v[82:85]
	v_mfma_f32_16x16x32_bf16 v[54:57], v[114:117], v[134:137], v[54:57]
	v_mfma_f32_16x16x32_bf16 v[58:61], v[122:125], v[134:137], v[58:61]
	v_mfma_f32_16x16x32_bf16 v[62:65], v[114:117], v[180:183], v[62:65]
	v_mfma_f32_16x16x32_bf16 v[66:69], v[122:125], v[180:183], v[66:69]
	v_mfma_f32_16x16x32_bf16 v[70:73], v[114:117], v[188:191], v[70:73]
	v_mfma_f32_16x16x32_bf16 v[74:77], v[122:125], v[188:191], v[74:77]
	v_mfma_f32_16x16x32_bf16 v[78:81], v[114:117], v[208:211], v[78:81]
	v_mfma_f32_16x16x32_bf16 v[82:85], v[122:125], v[208:211], v[82:85]
	s_setprio 0
	s_barrier
	s_mov_b32 m0, s44
	v_lshl_add_u64 v[126:127], s[26:27], 0, v[128:129]
	ds_read_b128 v[212:215], v198
	ds_read_b128 v[216:219], v198 offset:1024
	ds_read_b128 v[220:223], v198 offset:2048
	ds_read_b128 v[224:227], v198 offset:3072
	global_load_lds_dwordx4 v[126:127], off
	v_lshl_add_u64 v[228:229], s[26:27], 0, v[0:1]
	s_mov_b32 m0, s17
	s_nop 0
	global_load_lds_dwordx4 v[228:229], off
	s_barrier
	s_waitcnt lgkmcnt(0)
	s_setprio 1
	s_waitcnt lgkmcnt(0)
	v_mfma_f32_16x16x32_bf16 v[102:105], v[212:215], v[130:133], v[102:105]
	v_mfma_f32_16x16x32_bf16 v[22:25], v[220:223], v[130:133], v[22:25]
	v_mfma_f32_16x16x32_bf16 v[26:29], v[212:215], v[176:179], v[26:29]
	v_mfma_f32_16x16x32_bf16 v[30:33], v[220:223], v[176:179], v[30:33]
	v_mfma_f32_16x16x32_bf16 v[34:37], v[212:215], v[184:187], v[34:37]
	v_mfma_f32_16x16x32_bf16 v[38:41], v[220:223], v[184:187], v[38:41]
	v_mfma_f32_16x16x32_bf16 v[42:45], v[212:215], v[192:195], v[42:45]
	v_mfma_f32_16x16x32_bf16 v[46:49], v[220:223], v[192:195], v[46:49]
	v_mfma_f32_16x16x32_bf16 v[102:105], v[216:219], v[134:137], v[102:105]
	v_mfma_f32_16x16x32_bf16 v[22:25], v[224:227], v[134:137], v[22:25]
	v_mfma_f32_16x16x32_bf16 v[26:29], v[216:219], v[180:183], v[26:29]
	v_mfma_f32_16x16x32_bf16 v[30:33], v[224:227], v[180:183], v[30:33]
	v_mfma_f32_16x16x32_bf16 v[34:37], v[216:219], v[188:191], v[34:37]
	v_mfma_f32_16x16x32_bf16 v[38:41], v[224:227], v[188:191], v[38:41]
	v_mfma_f32_16x16x32_bf16 v[42:45], v[216:219], v[208:211], v[42:45]
	v_mfma_f32_16x16x32_bf16 v[46:49], v[224:227], v[208:211], v[46:49]
	s_setprio 0
	s_mov_b32 m0, s13
	v_lshl_add_u64 v[230:231], s[28:29], 0, v[128:129]
	s_barrier
	ds_read_b128 v[130:133], v5 offset:16384
	ds_read_b128 v[134:137], v5 offset:17408
	ds_read_b128 v[176:179], v5 offset:18432
	ds_read_b128 v[180:183], v5 offset:19456
	ds_read_b128 v[184:187], v5 offset:20480
	ds_read_b128 v[188:191], v5 offset:21504
	ds_read_b128 v[192:195], v5 offset:22528
	ds_read_b128 v[208:211], v5 offset:23552
	global_load_lds_dwordx4 v[230:231], off
	v_lshl_add_u64 v[232:233], s[28:29], 0, v[0:1]
	s_mov_b32 m0, s36
	s_nop 0
	global_load_lds_dwordx4 v[232:233], off
	s_barrier
	s_waitcnt lgkmcnt(0)
	s_setprio 1
	s_waitcnt lgkmcnt(0)
	v_mfma_f32_16x16x32_bf16 v[138:141], v[110:113], v[130:133], v[138:141]
	v_mfma_f32_16x16x32_bf16 v[142:145], v[118:121], v[130:133], v[142:145]
	v_mfma_f32_16x16x32_bf16 v[146:149], v[110:113], v[176:179], v[146:149]
	v_mfma_f32_16x16x32_bf16 v[150:153], v[118:121], v[176:179], v[150:153]
	v_mfma_f32_16x16x32_bf16 v[154:157], v[110:113], v[184:187], v[154:157]
	v_mfma_f32_16x16x32_bf16 v[158:161], v[118:121], v[184:187], v[158:161]
	v_mfma_f32_16x16x32_bf16 v[6:9], v[110:113], v[192:195], v[6:9]
	v_mfma_f32_16x16x32_bf16 v[10:13], v[118:121], v[192:195], v[10:13]
	v_mfma_f32_16x16x32_bf16 v[138:141], v[114:117], v[134:137], v[138:141]
	v_mfma_f32_16x16x32_bf16 v[142:145], v[122:125], v[134:137], v[142:145]
	v_mfma_f32_16x16x32_bf16 v[146:149], v[114:117], v[180:183], v[146:149]
	v_mfma_f32_16x16x32_bf16 v[150:153], v[122:125], v[180:183], v[150:153]
	v_mfma_f32_16x16x32_bf16 v[154:157], v[114:117], v[188:191], v[154:157]
	v_mfma_f32_16x16x32_bf16 v[158:161], v[122:125], v[188:191], v[158:161]
	v_mfma_f32_16x16x32_bf16 v[6:9], v[114:117], v[208:211], v[6:9]
	v_mfma_f32_16x16x32_bf16 v[10:13], v[122:125], v[208:211], v[10:13]
	s_setprio 0
	s_barrier
	s_add_u32 s22, s26, 0x10000
	s_addc_u32 s23, s27, 0
	s_mov_b32 m0, s46
	v_lshl_add_u64 v[110:111], s[22:23], 0, v[128:129]
	global_load_lds_dwordx4 v[110:111], off
	v_lshl_add_u64 v[110:111], s[22:23], 0, v[0:1]
	s_mov_b32 m0, s43
	s_nop 0
	global_load_lds_dwordx4 v[110:111], off
	s_waitcnt vmcnt(6)
	s_barrier
	s_setprio 1
	v_mfma_f32_16x16x32_bf16 v[14:17], v[212:215], v[130:133], v[14:17]
	v_mfma_f32_16x16x32_bf16 v[18:21], v[220:223], v[130:133], v[18:21]
	v_mfma_f32_16x16x32_bf16 v[50:53], v[212:215], v[176:179], v[50:53]
	v_mfma_f32_16x16x32_bf16 v[94:97], v[220:223], v[176:179], v[94:97]
	v_mfma_f32_16x16x32_bf16 v[98:101], v[212:215], v[184:187], v[98:101]
	v_mfma_f32_16x16x32_bf16 v[106:109], v[220:223], v[184:187], v[106:109]
	v_mfma_f32_16x16x32_bf16 v[86:89], v[212:215], v[192:195], v[86:89]
	v_mfma_f32_16x16x32_bf16 v[90:93], v[220:223], v[192:195], v[90:93]
	v_mfma_f32_16x16x32_bf16 v[14:17], v[216:219], v[134:137], v[14:17]
	v_mfma_f32_16x16x32_bf16 v[18:21], v[224:227], v[134:137], v[18:21]
	v_mfma_f32_16x16x32_bf16 v[50:53], v[216:219], v[180:183], v[50:53]
	v_mfma_f32_16x16x32_bf16 v[94:97], v[224:227], v[180:183], v[94:97]
	v_mfma_f32_16x16x32_bf16 v[98:101], v[216:219], v[188:191], v[98:101]
	v_mfma_f32_16x16x32_bf16 v[106:109], v[224:227], v[188:191], v[106:109]
	v_mfma_f32_16x16x32_bf16 v[86:89], v[216:219], v[208:211], v[86:89]
	v_mfma_f32_16x16x32_bf16 v[90:93], v[224:227], v[208:211], v[90:93]
	s_setprio 0
	s_barrier
	ds_read_b128 v[110:113], v200
	ds_read_b128 v[114:117], v200 offset:1024
	ds_read_b128 v[118:121], v200 offset:2048
	ds_read_b128 v[122:125], v200 offset:3072
	s_add_u32 s22, s28, 0x10000
	s_addc_u32 s23, s29, 0
	s_mov_b32 m0, s37
	v_lshl_add_u64 v[212:213], s[22:23], 0, v[128:129]
	ds_read_b128 v[130:133], v5 offset:32768
	ds_read_b128 v[134:137], v5 offset:33792
	ds_read_b128 v[176:179], v5 offset:34816
	ds_read_b128 v[180:183], v5 offset:35840
	ds_read_b128 v[184:187], v5 offset:36864
	ds_read_b128 v[188:191], v5 offset:37888
	ds_read_b128 v[192:195], v5 offset:38912
	ds_read_b128 v[208:211], v5 offset:39936
	global_load_lds_dwordx4 v[212:213], off
	v_lshl_add_u64 v[212:213], s[22:23], 0, v[0:1]
	s_mov_b32 m0, s38
	s_nop 0
	global_load_lds_dwordx4 v[212:213], off
	s_waitcnt lgkmcnt(8)
	s_barrier
	s_waitcnt lgkmcnt(0)
	s_setprio 1
	s_waitcnt lgkmcnt(0)
	v_mfma_f32_16x16x32_bf16 v[54:57], v[110:113], v[130:133], v[54:57]
	v_mfma_f32_16x16x32_bf16 v[58:61], v[118:121], v[130:133], v[58:61]
	v_mfma_f32_16x16x32_bf16 v[62:65], v[110:113], v[176:179], v[62:65]
	v_mfma_f32_16x16x32_bf16 v[66:69], v[118:121], v[176:179], v[66:69]
	v_mfma_f32_16x16x32_bf16 v[70:73], v[110:113], v[184:187], v[70:73]
	v_mfma_f32_16x16x32_bf16 v[74:77], v[118:121], v[184:187], v[74:77]
	v_mfma_f32_16x16x32_bf16 v[78:81], v[110:113], v[192:195], v[78:81]
	v_mfma_f32_16x16x32_bf16 v[82:85], v[118:121], v[192:195], v[82:85]
	v_mfma_f32_16x16x32_bf16 v[54:57], v[114:117], v[134:137], v[54:57]
	v_mfma_f32_16x16x32_bf16 v[58:61], v[122:125], v[134:137], v[58:61]
	v_mfma_f32_16x16x32_bf16 v[62:65], v[114:117], v[180:183], v[62:65]
	v_mfma_f32_16x16x32_bf16 v[66:69], v[122:125], v[180:183], v[66:69]
	v_mfma_f32_16x16x32_bf16 v[70:73], v[114:117], v[188:191], v[70:73]
	v_mfma_f32_16x16x32_bf16 v[74:77], v[122:125], v[188:191], v[74:77]
	v_mfma_f32_16x16x32_bf16 v[78:81], v[114:117], v[208:211], v[78:81]
	v_mfma_f32_16x16x32_bf16 v[82:85], v[122:125], v[208:211], v[82:85]
	s_setprio 0
	s_barrier
	s_mov_b32 m0, s48
	v_lshl_add_u64 v[126:127], v[126:127], 0, s[6:7]
	ds_read_b128 v[212:215], v234
	ds_read_b128 v[216:219], v234 offset:1024
	ds_read_b128 v[220:223], v234 offset:2048
	ds_read_b128 v[224:227], v234 offset:3072
	global_load_lds_dwordx4 v[126:127], off
	v_lshl_add_u64 v[126:127], v[228:229], 0, s[6:7]
	s_mov_b32 m0, s47
	s_nop 0
	global_load_lds_dwordx4 v[126:127], off
	s_barrier
	s_waitcnt lgkmcnt(0)
	s_setprio 1
	s_waitcnt lgkmcnt(0)
	v_mfma_f32_16x16x32_bf16 v[102:105], v[212:215], v[130:133], v[102:105]
	v_mfma_f32_16x16x32_bf16 v[22:25], v[220:223], v[130:133], v[22:25]
	v_mfma_f32_16x16x32_bf16 v[26:29], v[212:215], v[176:179], v[26:29]
	v_mfma_f32_16x16x32_bf16 v[30:33], v[220:223], v[176:179], v[30:33]
	v_mfma_f32_16x16x32_bf16 v[34:37], v[212:215], v[184:187], v[34:37]
	v_mfma_f32_16x16x32_bf16 v[38:41], v[220:223], v[184:187], v[38:41]
	v_mfma_f32_16x16x32_bf16 v[42:45], v[212:215], v[192:195], v[42:45]
	v_mfma_f32_16x16x32_bf16 v[46:49], v[220:223], v[192:195], v[46:49]
	v_mfma_f32_16x16x32_bf16 v[102:105], v[216:219], v[134:137], v[102:105]
	v_mfma_f32_16x16x32_bf16 v[22:25], v[224:227], v[134:137], v[22:25]
	v_mfma_f32_16x16x32_bf16 v[26:29], v[216:219], v[180:183], v[26:29]
	v_mfma_f32_16x16x32_bf16 v[30:33], v[224:227], v[180:183], v[30:33]
	v_mfma_f32_16x16x32_bf16 v[34:37], v[216:219], v[188:191], v[34:37]
	v_mfma_f32_16x16x32_bf16 v[38:41], v[224:227], v[188:191], v[38:41]
	v_mfma_f32_16x16x32_bf16 v[42:45], v[216:219], v[208:211], v[42:45]
	v_mfma_f32_16x16x32_bf16 v[46:49], v[224:227], v[208:211], v[46:49]
	s_setprio 0
	s_mov_b32 m0, s39
	v_lshl_add_u64 v[126:127], v[230:231], 0, s[6:7]
	s_barrier
	ds_read_b128 v[130:133], v5 offset:49152
	ds_read_b128 v[134:137], v5 offset:50176
	ds_read_b128 v[176:179], v5 offset:51200
	ds_read_b128 v[180:183], v5 offset:52224
	ds_read_b128 v[184:187], v5 offset:53248
	ds_read_b128 v[188:191], v5 offset:54272
	ds_read_b128 v[192:195], v5 offset:55296
	ds_read_b128 v[208:211], v5 offset:56320
	global_load_lds_dwordx4 v[126:127], off
	v_lshl_add_u64 v[126:127], v[232:233], 0, s[6:7]
	s_mov_b32 m0, s40
	s_nop 0
	global_load_lds_dwordx4 v[126:127], off
	s_barrier
	s_waitcnt lgkmcnt(0)
	s_setprio 1
	s_waitcnt lgkmcnt(0)
	v_mfma_f32_16x16x32_bf16 v[138:141], v[110:113], v[130:133], v[138:141]
	v_mfma_f32_16x16x32_bf16 v[142:145], v[118:121], v[130:133], v[142:145]
	v_mfma_f32_16x16x32_bf16 v[146:149], v[110:113], v[176:179], v[146:149]
	v_mfma_f32_16x16x32_bf16 v[150:153], v[118:121], v[176:179], v[150:153]
	v_mfma_f32_16x16x32_bf16 v[154:157], v[110:113], v[184:187], v[154:157]
	v_mfma_f32_16x16x32_bf16 v[158:161], v[118:121], v[184:187], v[158:161]
	v_mfma_f32_16x16x32_bf16 v[6:9], v[110:113], v[192:195], v[6:9]
	v_mfma_f32_16x16x32_bf16 v[10:13], v[118:121], v[192:195], v[10:13]
	v_mfma_f32_16x16x32_bf16 v[138:141], v[114:117], v[134:137], v[138:141]
	v_mfma_f32_16x16x32_bf16 v[142:145], v[122:125], v[134:137], v[142:145]
	v_mfma_f32_16x16x32_bf16 v[146:149], v[114:117], v[180:183], v[146:149]
	v_mfma_f32_16x16x32_bf16 v[150:153], v[122:125], v[180:183], v[150:153]
	v_mfma_f32_16x16x32_bf16 v[154:157], v[114:117], v[188:191], v[154:157]
	v_mfma_f32_16x16x32_bf16 v[158:161], v[122:125], v[188:191], v[158:161]
	v_mfma_f32_16x16x32_bf16 v[6:9], v[114:117], v[208:211], v[6:9]
	v_mfma_f32_16x16x32_bf16 v[10:13], v[122:125], v[208:211], v[10:13]
	s_setprio 0
	s_barrier
	s_add_u32 s22, s26, 0x10080
	s_addc_u32 s23, s27, 0
	s_mov_b32 m0, s25
	v_lshl_add_u64 v[110:111], s[22:23], 0, v[128:129]
	global_load_lds_dwordx4 v[110:111], off
	v_lshl_add_u64 v[110:111], s[22:23], 0, v[0:1]
	s_mov_b32 m0, s24
	s_nop 0
	global_load_lds_dwordx4 v[110:111], off
	s_waitcnt vmcnt(6)
	s_barrier
	s_setprio 1
	v_mfma_f32_16x16x32_bf16 v[14:17], v[212:215], v[130:133], v[14:17]
	v_mfma_f32_16x16x32_bf16 v[18:21], v[220:223], v[130:133], v[18:21]
	v_mfma_f32_16x16x32_bf16 v[50:53], v[212:215], v[176:179], v[50:53]
	v_mfma_f32_16x16x32_bf16 v[94:97], v[220:223], v[176:179], v[94:97]
	v_mfma_f32_16x16x32_bf16 v[98:101], v[212:215], v[184:187], v[98:101]
	v_mfma_f32_16x16x32_bf16 v[106:109], v[220:223], v[184:187], v[106:109]
	v_mfma_f32_16x16x32_bf16 v[86:89], v[212:215], v[192:195], v[86:89]
	v_mfma_f32_16x16x32_bf16 v[90:93], v[220:223], v[192:195], v[90:93]
	v_mfma_f32_16x16x32_bf16 v[14:17], v[216:219], v[134:137], v[14:17]
	v_mfma_f32_16x16x32_bf16 v[18:21], v[224:227], v[134:137], v[18:21]
	v_mfma_f32_16x16x32_bf16 v[50:53], v[216:219], v[180:183], v[50:53]
	v_mfma_f32_16x16x32_bf16 v[94:97], v[224:227], v[180:183], v[94:97]
	v_mfma_f32_16x16x32_bf16 v[98:101], v[216:219], v[188:191], v[98:101]
	v_mfma_f32_16x16x32_bf16 v[106:109], v[224:227], v[188:191], v[106:109]
	v_mfma_f32_16x16x32_bf16 v[86:89], v[216:219], v[208:211], v[86:89]
	v_mfma_f32_16x16x32_bf16 v[90:93], v[224:227], v[208:211], v[90:93]
	s_setprio 0
	v_lshl_add_u32 v110, s12, 8, v2
	v_lshl_or_b32 v112, s41, 8, v4
	v_ashrrev_i32_e32 v111, 31, v110
	v_readlane_b32 s48, v255, 37
	v_ashrrev_i32_e32 v113, 31, v112
	v_lshlrev_b64 v[114:115], 13, v[110:111]
	v_readlane_b32 s49, v255, 38
	v_lshlrev_b64 v[112:113], 2, v[112:113]
	s_barrier
	v_lshl_add_u64 v[114:115], s[48:49], 0, v[114:115]
	v_lshl_add_u64 v[114:115], v[114:115], 0, v[112:113]
	global_store_dwordx4 v[114:115], v[54:57], off
	global_store_dwordx4 v[114:115], v[58:61], off offset:64
	global_store_dwordx4 v[114:115], v[102:105], off offset:512
	global_store_dwordx4 v[114:115], v[22:25], off offset:576
	s_mov_b64 s[22:23], 0x100000
	s_add_i32 s42, s42, s68
	v_or_b32_e32 v22, 16, v110
	v_ashrrev_i32_e32 v23, 31, v22
	v_lshlrev_b64 v[22:23], 13, v[22:23]
	v_lshl_add_u64 v[22:23], s[48:49], 0, v[22:23]
	v_lshl_add_u64 v[22:23], v[22:23], 0, v[112:113]
	global_store_dwordx4 v[22:23], v[62:65], off
	global_store_dwordx4 v[22:23], v[66:69], off offset:64
	global_store_dwordx4 v[22:23], v[26:29], off offset:512
	global_store_dwordx4 v[22:23], v[30:33], off offset:576
	v_or_b32_e32 v22, 32, v110
	v_ashrrev_i32_e32 v23, 31, v22
	v_lshlrev_b64 v[22:23], 13, v[22:23]
	v_lshl_add_u64 v[22:23], s[48:49], 0, v[22:23]
	v_lshl_add_u64 v[22:23], v[22:23], 0, v[112:113]
	global_store_dwordx4 v[22:23], v[70:73], off
	global_store_dwordx4 v[22:23], v[74:77], off offset:64
	global_store_dwordx4 v[22:23], v[34:37], off offset:512
	global_store_dwordx4 v[22:23], v[38:41], off offset:576
	v_or_b32_e32 v22, 48, v110
	v_ashrrev_i32_e32 v23, 31, v22
	v_lshlrev_b64 v[22:23], 13, v[22:23]
	v_lshl_add_u64 v[22:23], s[48:49], 0, v[22:23]
	v_add_co_u32_e32 v24, vcc, s90, v114
	v_lshl_add_u64 v[22:23], v[22:23], 0, v[112:113]
	s_nop 0
	v_addc_co_u32_e32 v25, vcc, 0, v115, vcc
	global_store_dwordx4 v[22:23], v[78:81], off
	global_store_dwordx4 v[22:23], v[82:85], off offset:64
	global_store_dwordx4 v[22:23], v[42:45], off offset:512
	global_store_dwordx4 v[22:23], v[46:49], off offset:576
	v_lshl_add_u64 v[22:23], v[114:115], 0, s[22:23]
	global_store_dwordx4 v[24:25], v[138:141], off
	global_store_dwordx4 v[22:23], v[142:145], off offset:64
	global_store_dwordx4 v[22:23], v[14:17], off offset:512
	global_store_dwordx4 v[22:23], v[18:21], off offset:576
	s_mov_b64 s[22:23], 0x120000
	v_add_co_u32_e32 v16, vcc, s91, v114
	v_lshl_add_u64 v[14:15], v[114:115], 0, s[22:23]
	s_nop 0
	v_addc_co_u32_e32 v17, vcc, 0, v115, vcc
	global_store_dwordx4 v[16:17], v[146:149], off
	global_store_dwordx4 v[14:15], v[150:153], off offset:64
	global_store_dwordx4 v[14:15], v[50:53], off offset:512
	global_store_dwordx4 v[14:15], v[94:97], off offset:576
	v_add_co_u32_e32 v16, vcc, s96, v114
	s_mov_b64 s[22:23], 0x140000
	s_nop 0
	v_addc_co_u32_e32 v17, vcc, 0, v115, vcc
	v_lshl_add_u64 v[14:15], v[114:115], 0, s[22:23]
	global_store_dwordx4 v[16:17], v[154:157], off
	global_store_dwordx4 v[14:15], v[158:161], off offset:64
	global_store_dwordx4 v[14:15], v[98:101], off offset:512
	global_store_dwordx4 v[14:15], v[106:109], off offset:576
	v_add_co_u32_e32 v16, vcc, 0x160000, v114
	s_mov_b64 s[22:23], 0x160000
	s_nop 0
	v_addc_co_u32_e32 v17, vcc, 0, v115, vcc
	v_lshl_add_u64 v[14:15], v[114:115], 0, s[22:23]
	s_andn2_b64 vcc, exec, s[8:9]
	s_mov_b32 s41, s14
	s_mov_b32 s12, s16
	s_mov_b64 s[24:25], s[20:21]
	s_mov_b64 s[22:23], s[18:19]
	global_store_dwordx4 v[16:17], v[6:9], off
	global_store_dwordx4 v[14:15], v[10:13], off offset:64
	global_store_dwordx4 v[14:15], v[86:89], off offset:512
	global_store_dwordx4 v[14:15], v[90:93], off offset:576
	s_cbranch_vccz .LBB0_84
	.p2align 6

.LBB0_101:
	s_ashr_i32 s13, s12, 31
	v_cmp_lt_i64_e32 vcc, s[14:15], v[166:167]
	s_lshl_b64 s[14:15], s[12:13], 20
	v_readlane_b32 s16, v255, 34
	v_readlane_b32 s17, v255, 35
	s_add_u32 s14, s16, s14
	s_addc_u32 s15, s17, s15
	s_and_b64 s[16:17], vcc, exec
	s_cselect_b32 s13, s15, s21
	s_cselect_b32 s39, s14, s20
	s_ashr_i32 s11, s10, 31
	s_lshl_b64 s[16:17], s[10:11], 20
	s_add_u32 s16, s27, s16
	s_addc_u32 s17, s28, s17
	s_and_b64 s[24:25], vcc, exec
	s_cselect_b32 s11, s17, s23
	s_cselect_b32 s40, s16, s22
	s_add_u32 s20, s20, 0x80080
	s_addc_u32 s21, s21, 0
	s_add_u32 s41, s22, 0x100
	v_mov_b32_e32 v0, 0
	s_addc_u32 s42, s23, 0
	s_mov_b32 s43, -2
	v_mov_b32_e32 v1, v0
	v_mov_b32_e32 v2, v0
	v_mov_b32_e32 v3, v0
	v_mov_b32_e32 v4, v0
	v_mov_b32_e32 v5, v0
	v_mov_b32_e32 v6, v0
	v_mov_b32_e32 v7, v0
	v_mov_b32_e32 v16, v0
	v_mov_b32_e32 v17, v0
	v_mov_b32_e32 v18, v0
	v_mov_b32_e32 v19, v0
	v_mov_b32_e32 v20, v0
	v_mov_b32_e32 v21, v0
	v_mov_b32_e32 v22, v0
	v_mov_b32_e32 v23, v0
	v_mov_b32_e32 v32, v0
	v_mov_b32_e32 v33, v0
	v_mov_b32_e32 v34, v0
	v_mov_b32_e32 v35, v0
	v_mov_b32_e32 v36, v0
	v_mov_b32_e32 v37, v0
	v_mov_b32_e32 v38, v0
	v_mov_b32_e32 v39, v0
	v_mov_b32_e32 v48, v0
	v_mov_b32_e32 v49, v0
	v_mov_b32_e32 v50, v0
	v_mov_b32_e32 v51, v0
	v_mov_b32_e32 v52, v0
	v_mov_b32_e32 v53, v0
	v_mov_b32_e32 v54, v0
	v_mov_b32_e32 v55, v0
	v_mov_b32_e32 v8, v0
	v_mov_b32_e32 v9, v0
	v_mov_b32_e32 v10, v0
	v_mov_b32_e32 v11, v0
	v_mov_b32_e32 v12, v0
	v_mov_b32_e32 v13, v0
	v_mov_b32_e32 v14, v0
	v_mov_b32_e32 v15, v0
	v_mov_b32_e32 v24, v0
	v_mov_b32_e32 v25, v0
	v_mov_b32_e32 v26, v0
	v_mov_b32_e32 v27, v0
	v_mov_b32_e32 v28, v0
	v_mov_b32_e32 v29, v0
	v_mov_b32_e32 v30, v0
	v_mov_b32_e32 v31, v0
	v_mov_b32_e32 v40, v0
	v_mov_b32_e32 v41, v0
	v_mov_b32_e32 v42, v0
	v_mov_b32_e32 v43, v0
	v_mov_b32_e32 v44, v0
	v_mov_b32_e32 v45, v0
	v_mov_b32_e32 v46, v0
	v_mov_b32_e32 v47, v0
	v_mov_b32_e32 v56, v0
	v_mov_b32_e32 v57, v0
	v_mov_b32_e32 v58, v0
	v_mov_b32_e32 v59, v0
	v_mov_b32_e32 v60, v0
	v_mov_b32_e32 v61, v0
	v_mov_b32_e32 v62, v0
	v_mov_b32_e32 v63, v0
	v_mov_b32_e32 v64, v0
	v_mov_b32_e32 v65, v0
	v_mov_b32_e32 v66, v0
	v_mov_b32_e32 v67, v0
	v_mov_b32_e32 v68, v0
	v_mov_b32_e32 v69, v0
	v_mov_b32_e32 v70, v0
	v_mov_b32_e32 v71, v0
	v_mov_b32_e32 v80, v0
	v_mov_b32_e32 v81, v0
	v_mov_b32_e32 v82, v0
	v_mov_b32_e32 v83, v0
	v_mov_b32_e32 v84, v0
	v_mov_b32_e32 v85, v0
	v_mov_b32_e32 v86, v0
	v_mov_b32_e32 v87, v0
	v_mov_b32_e32 v96, v0
	v_mov_b32_e32 v97, v0
	v_mov_b32_e32 v98, v0
	v_mov_b32_e32 v99, v0
	v_mov_b32_e32 v100, v0
	v_mov_b32_e32 v101, v0
	v_mov_b32_e32 v102, v0
	v_mov_b32_e32 v103, v0
	v_mov_b32_e32 v112, v0
	v_mov_b32_e32 v113, v0
	v_mov_b32_e32 v114, v0
	v_mov_b32_e32 v115, v0
	v_mov_b32_e32 v116, v0
	v_mov_b32_e32 v117, v0
	v_mov_b32_e32 v118, v0
	v_mov_b32_e32 v119, v0
	v_mov_b32_e32 v72, v0
	v_mov_b32_e32 v73, v0
	v_mov_b32_e32 v74, v0
	v_mov_b32_e32 v75, v0
	v_mov_b32_e32 v76, v0
	v_mov_b32_e32 v77, v0
	v_mov_b32_e32 v78, v0
	v_mov_b32_e32 v79, v0
	v_mov_b32_e32 v88, v0
	v_mov_b32_e32 v89, v0
	v_mov_b32_e32 v90, v0
	v_mov_b32_e32 v91, v0
	v_mov_b32_e32 v92, v0
	v_mov_b32_e32 v93, v0
	v_mov_b32_e32 v94, v0
	v_mov_b32_e32 v95, v0
	v_mov_b32_e32 v104, v0
	v_mov_b32_e32 v105, v0
	v_mov_b32_e32 v106, v0
	v_mov_b32_e32 v107, v0
	v_mov_b32_e32 v108, v0
	v_mov_b32_e32 v109, v0
	v_mov_b32_e32 v110, v0
	v_mov_b32_e32 v111, v0
	v_mov_b32_e32 v120, v0
	v_mov_b32_e32 v121, v0
	v_mov_b32_e32 v122, v0
	v_mov_b32_e32 v123, v0
	v_mov_b32_e32 v124, v0
	v_mov_b32_e32 v125, v0
	v_mov_b32_e32 v126, v0
	v_mov_b32_e32 v127, v0
	.p2align 6

.LBB0_128:
	s_add_u32 s39, s16, 0x100
	v_mov_b32_e32 v0, 0
	s_addc_u32 s40, s17, 0
	s_mov_b32 s41, -2
	v_mov_b32_e32 v1, v0
	v_mov_b32_e32 v2, v0
	v_mov_b32_e32 v3, v0
	v_mov_b32_e32 v4, v0
	v_mov_b32_e32 v5, v0
	v_mov_b32_e32 v6, v0
	v_mov_b32_e32 v7, v0
	v_mov_b32_e32 v16, v0
	v_mov_b32_e32 v17, v0
	v_mov_b32_e32 v18, v0
	v_mov_b32_e32 v19, v0
	v_mov_b32_e32 v20, v0
	v_mov_b32_e32 v21, v0
	v_mov_b32_e32 v22, v0
	v_mov_b32_e32 v23, v0
	v_mov_b32_e32 v32, v0
	v_mov_b32_e32 v33, v0
	v_mov_b32_e32 v34, v0
	v_mov_b32_e32 v35, v0
	v_mov_b32_e32 v36, v0
	v_mov_b32_e32 v37, v0
	v_mov_b32_e32 v38, v0
	v_mov_b32_e32 v39, v0
	v_mov_b32_e32 v48, v0
	v_mov_b32_e32 v49, v0
	v_mov_b32_e32 v50, v0
	v_mov_b32_e32 v51, v0
	v_mov_b32_e32 v52, v0
	v_mov_b32_e32 v53, v0
	v_mov_b32_e32 v54, v0
	v_mov_b32_e32 v55, v0
	v_mov_b32_e32 v8, v0
	v_mov_b32_e32 v9, v0
	v_mov_b32_e32 v10, v0
	v_mov_b32_e32 v11, v0
	v_mov_b32_e32 v12, v0
	v_mov_b32_e32 v13, v0
	v_mov_b32_e32 v14, v0
	v_mov_b32_e32 v15, v0
	v_mov_b32_e32 v24, v0
	v_mov_b32_e32 v25, v0
	v_mov_b32_e32 v26, v0
	v_mov_b32_e32 v27, v0
	v_mov_b32_e32 v28, v0
	v_mov_b32_e32 v29, v0
	v_mov_b32_e32 v30, v0
	v_mov_b32_e32 v31, v0
	v_mov_b32_e32 v40, v0
	v_mov_b32_e32 v41, v0
	v_mov_b32_e32 v42, v0
	v_mov_b32_e32 v43, v0
	v_mov_b32_e32 v44, v0
	v_mov_b32_e32 v45, v0
	v_mov_b32_e32 v46, v0
	v_mov_b32_e32 v47, v0
	v_mov_b32_e32 v56, v0
	v_mov_b32_e32 v57, v0
	v_mov_b32_e32 v58, v0
	v_mov_b32_e32 v59, v0
	v_mov_b32_e32 v60, v0
	v_mov_b32_e32 v61, v0
	v_mov_b32_e32 v62, v0
	v_mov_b32_e32 v63, v0
	v_mov_b32_e32 v64, v0
	v_mov_b32_e32 v65, v0
	v_mov_b32_e32 v66, v0
	v_mov_b32_e32 v67, v0
	v_mov_b32_e32 v68, v0
	v_mov_b32_e32 v69, v0
	v_mov_b32_e32 v70, v0
	v_mov_b32_e32 v71, v0
	v_mov_b32_e32 v80, v0
	v_mov_b32_e32 v81, v0
	v_mov_b32_e32 v82, v0
	v_mov_b32_e32 v83, v0
	v_mov_b32_e32 v84, v0
	v_mov_b32_e32 v85, v0
	v_mov_b32_e32 v86, v0
	v_mov_b32_e32 v87, v0
	v_mov_b32_e32 v96, v0
	v_mov_b32_e32 v97, v0
	v_mov_b32_e32 v98, v0
	v_mov_b32_e32 v99, v0
	v_mov_b32_e32 v100, v0
	v_mov_b32_e32 v101, v0
	v_mov_b32_e32 v102, v0
	v_mov_b32_e32 v103, v0
	v_mov_b32_e32 v112, v0
	v_mov_b32_e32 v113, v0
	v_mov_b32_e32 v114, v0
	v_mov_b32_e32 v115, v0
	v_mov_b32_e32 v116, v0
	v_mov_b32_e32 v117, v0
	v_mov_b32_e32 v118, v0
	v_mov_b32_e32 v119, v0
	v_mov_b32_e32 v72, v0
	v_mov_b32_e32 v73, v0
	v_mov_b32_e32 v74, v0
	v_mov_b32_e32 v75, v0
	v_mov_b32_e32 v76, v0
	v_mov_b32_e32 v77, v0
	v_mov_b32_e32 v78, v0
	v_mov_b32_e32 v79, v0
	v_mov_b32_e32 v88, v0
	v_mov_b32_e32 v89, v0
	v_mov_b32_e32 v90, v0
	v_mov_b32_e32 v91, v0
	v_mov_b32_e32 v92, v0
	v_mov_b32_e32 v93, v0
	v_mov_b32_e32 v94, v0
	v_mov_b32_e32 v95, v0
	v_mov_b32_e32 v104, v0
	v_mov_b32_e32 v105, v0
	v_mov_b32_e32 v106, v0
	v_mov_b32_e32 v107, v0
	v_mov_b32_e32 v108, v0
	v_mov_b32_e32 v109, v0
	v_mov_b32_e32 v110, v0
	v_mov_b32_e32 v111, v0
	v_mov_b32_e32 v120, v0
	v_mov_b32_e32 v121, v0
	v_mov_b32_e32 v122, v0
	v_mov_b32_e32 v123, v0
	v_mov_b32_e32 v124, v0
	v_mov_b32_e32 v125, v0
	v_mov_b32_e32 v126, v0
	v_mov_b32_e32 v127, v0
	.p2align 6

.LBB0_142:
	s_ashr_i32 s13, s12, 31
	v_cmp_lt_i64_e32 vcc, s[14:15], v[170:171]
	s_lshl_b64 s[14:15], s[12:13], 20
	v_readlane_b32 s16, v255, 34
	v_readlane_b32 s17, v255, 35
	s_add_u32 s14, s16, s14
	s_addc_u32 s15, s17, s15
	s_and_b64 s[16:17], vcc, exec
	s_cselect_b32 s13, s15, s21
	s_cselect_b32 s39, s14, s20
	s_ashr_i32 s11, s10, 31
	s_lshl_b64 s[16:17], s[10:11], 20
	s_add_u32 s16, s26, s16
	s_addc_u32 s17, s27, s17
	s_and_b64 s[24:25], vcc, exec
	s_cselect_b32 s11, s17, s23
	s_cselect_b32 s40, s16, s22
	s_add_u32 s20, s20, 0x80080
	s_addc_u32 s21, s21, 0
	s_add_u32 s41, s22, 0x100
	v_mov_b32_e32 v0, 0
	s_addc_u32 s42, s23, 0
	s_mov_b32 s43, -2
	v_mov_b32_e32 v1, v0
	v_mov_b32_e32 v2, v0
	v_mov_b32_e32 v3, v0
	v_mov_b32_e32 v8, v0
	v_mov_b32_e32 v9, v0
	v_mov_b32_e32 v10, v0
	v_mov_b32_e32 v11, v0
	v_mov_b32_e32 v16, v0
	v_mov_b32_e32 v17, v0
	v_mov_b32_e32 v18, v0
	v_mov_b32_e32 v19, v0
	v_mov_b32_e32 v24, v0
	v_mov_b32_e32 v25, v0
	v_mov_b32_e32 v26, v0
	v_mov_b32_e32 v27, v0
	v_mov_b32_e32 v32, v0
	v_mov_b32_e32 v33, v0
	v_mov_b32_e32 v34, v0
	v_mov_b32_e32 v35, v0
	v_mov_b32_e32 v40, v0
	v_mov_b32_e32 v41, v0
	v_mov_b32_e32 v42, v0
	v_mov_b32_e32 v43, v0
	v_mov_b32_e32 v48, v0
	v_mov_b32_e32 v49, v0
	v_mov_b32_e32 v50, v0
	v_mov_b32_e32 v51, v0
	v_mov_b32_e32 v56, v0
	v_mov_b32_e32 v57, v0
	v_mov_b32_e32 v58, v0
	v_mov_b32_e32 v59, v0
	v_mov_b32_e32 v4, v0
	v_mov_b32_e32 v5, v0
	v_mov_b32_e32 v6, v0
	v_mov_b32_e32 v7, v0
	v_mov_b32_e32 v12, v0
	v_mov_b32_e32 v13, v0
	v_mov_b32_e32 v14, v0
	v_mov_b32_e32 v15, v0
	v_mov_b32_e32 v20, v0
	v_mov_b32_e32 v21, v0
	v_mov_b32_e32 v22, v0
	v_mov_b32_e32 v23, v0
	v_mov_b32_e32 v28, v0
	v_mov_b32_e32 v29, v0
	v_mov_b32_e32 v30, v0
	v_mov_b32_e32 v31, v0
	v_mov_b32_e32 v36, v0
	v_mov_b32_e32 v37, v0
	v_mov_b32_e32 v38, v0
	v_mov_b32_e32 v39, v0
	v_mov_b32_e32 v44, v0
	v_mov_b32_e32 v45, v0
	v_mov_b32_e32 v46, v0
	v_mov_b32_e32 v47, v0
	v_mov_b32_e32 v52, v0
	v_mov_b32_e32 v53, v0
	v_mov_b32_e32 v54, v0
	v_mov_b32_e32 v55, v0
	v_mov_b32_e32 v60, v0
	v_mov_b32_e32 v61, v0
	v_mov_b32_e32 v62, v0
	v_mov_b32_e32 v63, v0
	v_mov_b32_e32 v64, v0
	v_mov_b32_e32 v65, v0
	v_mov_b32_e32 v66, v0
	v_mov_b32_e32 v67, v0
	v_mov_b32_e32 v72, v0
	v_mov_b32_e32 v73, v0
	v_mov_b32_e32 v74, v0
	v_mov_b32_e32 v75, v0
	v_mov_b32_e32 v80, v0
	v_mov_b32_e32 v81, v0
	v_mov_b32_e32 v82, v0
	v_mov_b32_e32 v83, v0
	v_mov_b32_e32 v88, v0
	v_mov_b32_e32 v89, v0
	v_mov_b32_e32 v90, v0
	v_mov_b32_e32 v91, v0
	v_mov_b32_e32 v96, v0
	v_mov_b32_e32 v97, v0
	v_mov_b32_e32 v98, v0
	v_mov_b32_e32 v99, v0
	v_mov_b32_e32 v104, v0
	v_mov_b32_e32 v105, v0
	v_mov_b32_e32 v106, v0
	v_mov_b32_e32 v107, v0
	v_mov_b32_e32 v112, v0
	v_mov_b32_e32 v113, v0
	v_mov_b32_e32 v114, v0
	v_mov_b32_e32 v115, v0
	v_mov_b32_e32 v120, v0
	v_mov_b32_e32 v121, v0
	v_mov_b32_e32 v122, v0
	v_mov_b32_e32 v123, v0
	v_mov_b32_e32 v68, v0
	v_mov_b32_e32 v69, v0
	v_mov_b32_e32 v70, v0
	v_mov_b32_e32 v71, v0
	v_mov_b32_e32 v76, v0
	v_mov_b32_e32 v77, v0
	v_mov_b32_e32 v78, v0
	v_mov_b32_e32 v79, v0
	v_mov_b32_e32 v84, v0
	v_mov_b32_e32 v85, v0
	v_mov_b32_e32 v86, v0
	v_mov_b32_e32 v87, v0
	v_mov_b32_e32 v92, v0
	v_mov_b32_e32 v93, v0
	v_mov_b32_e32 v94, v0
	v_mov_b32_e32 v95, v0
	v_mov_b32_e32 v100, v0
	v_mov_b32_e32 v101, v0
	v_mov_b32_e32 v102, v0
	v_mov_b32_e32 v103, v0
	v_mov_b32_e32 v108, v0
	v_mov_b32_e32 v109, v0
	v_mov_b32_e32 v110, v0
	v_mov_b32_e32 v111, v0
	v_mov_b32_e32 v116, v0
	v_mov_b32_e32 v117, v0
	v_mov_b32_e32 v118, v0
	v_mov_b32_e32 v119, v0
	v_mov_b32_e32 v124, v0
	v_mov_b32_e32 v125, v0
	v_mov_b32_e32 v126, v0
	v_mov_b32_e32 v127, v0
	.p2align 6

.LBB0_166:
	s_ashr_i32 s13, s12, 31
	v_cmp_lt_i64_e32 vcc, s[14:15], v[166:167]
	s_lshl_b64 s[14:15], s[12:13], 20
	v_readlane_b32 s16, v255, 34
	v_readlane_b32 s17, v255, 35
	s_add_u32 s14, s16, s14
	s_addc_u32 s15, s17, s15
	s_and_b64 s[16:17], vcc, exec
	s_cselect_b32 s13, s15, s21
	s_cselect_b32 s41, s14, s20
	s_ashr_i32 s11, s10, 31
	s_lshl_b64 s[16:17], s[10:11], 20
	s_add_u32 s16, s29, s16
	s_addc_u32 s17, s30, s17
	s_and_b64 s[24:25], vcc, exec
	s_cselect_b32 s11, s17, s23
	s_cselect_b32 s42, s16, s22
	s_add_u32 s43, s22, 0x100
	v_mov_b32_e32 v0, 0
	s_addc_u32 s44, s23, 0
	s_mov_b32 s45, -2
	v_mov_b32_e32 v1, v0
	v_mov_b32_e32 v2, v0
	v_mov_b32_e32 v3, v0
	v_mov_b32_e32 v4, v0
	v_mov_b32_e32 v5, v0
	v_mov_b32_e32 v6, v0
	v_mov_b32_e32 v7, v0
	v_mov_b32_e32 v16, v0
	v_mov_b32_e32 v17, v0
	v_mov_b32_e32 v18, v0
	v_mov_b32_e32 v19, v0
	v_mov_b32_e32 v20, v0
	v_mov_b32_e32 v21, v0
	v_mov_b32_e32 v22, v0
	v_mov_b32_e32 v23, v0
	v_mov_b32_e32 v24, v0
	v_mov_b32_e32 v25, v0
	v_mov_b32_e32 v26, v0
	v_mov_b32_e32 v27, v0
	v_mov_b32_e32 v28, v0
	v_mov_b32_e32 v29, v0
	v_mov_b32_e32 v30, v0
	v_mov_b32_e32 v31, v0
	v_mov_b32_e32 v40, v0
	v_mov_b32_e32 v41, v0
	v_mov_b32_e32 v42, v0
	v_mov_b32_e32 v43, v0
	v_mov_b32_e32 v44, v0
	v_mov_b32_e32 v45, v0
	v_mov_b32_e32 v46, v0
	v_mov_b32_e32 v47, v0
	v_mov_b32_e32 v8, v0
	v_mov_b32_e32 v9, v0
	v_mov_b32_e32 v10, v0
	v_mov_b32_e32 v11, v0
	v_mov_b32_e32 v12, v0
	v_mov_b32_e32 v13, v0
	v_mov_b32_e32 v14, v0
	v_mov_b32_e32 v15, v0
	v_mov_b32_e32 v32, v0
	v_mov_b32_e32 v33, v0
	v_mov_b32_e32 v34, v0
	v_mov_b32_e32 v35, v0
	v_mov_b32_e32 v36, v0
	v_mov_b32_e32 v37, v0
	v_mov_b32_e32 v38, v0
	v_mov_b32_e32 v39, v0
	v_mov_b32_e32 v48, v0
	v_mov_b32_e32 v49, v0
	v_mov_b32_e32 v50, v0
	v_mov_b32_e32 v51, v0
	v_mov_b32_e32 v52, v0
	v_mov_b32_e32 v53, v0
	v_mov_b32_e32 v54, v0
	v_mov_b32_e32 v55, v0
	v_mov_b32_e32 v56, v0
	v_mov_b32_e32 v57, v0
	v_mov_b32_e32 v58, v0
	v_mov_b32_e32 v59, v0
	v_mov_b32_e32 v60, v0
	v_mov_b32_e32 v61, v0
	v_mov_b32_e32 v62, v0
	v_mov_b32_e32 v63, v0
	v_mov_b32_e32 v64, v0
	v_mov_b32_e32 v65, v0
	v_mov_b32_e32 v66, v0
	v_mov_b32_e32 v67, v0
	v_mov_b32_e32 v68, v0
	v_mov_b32_e32 v69, v0
	v_mov_b32_e32 v70, v0
	v_mov_b32_e32 v71, v0
	v_mov_b32_e32 v80, v0
	v_mov_b32_e32 v81, v0
	v_mov_b32_e32 v82, v0
	v_mov_b32_e32 v83, v0
	v_mov_b32_e32 v84, v0
	v_mov_b32_e32 v85, v0
	v_mov_b32_e32 v86, v0
	v_mov_b32_e32 v87, v0
	v_mov_b32_e32 v96, v0
	v_mov_b32_e32 v97, v0
	v_mov_b32_e32 v98, v0
	v_mov_b32_e32 v99, v0
	v_mov_b32_e32 v100, v0
	v_mov_b32_e32 v101, v0
	v_mov_b32_e32 v102, v0
	v_mov_b32_e32 v103, v0
	v_mov_b32_e32 v112, v0
	v_mov_b32_e32 v113, v0
	v_mov_b32_e32 v114, v0
	v_mov_b32_e32 v115, v0
	v_mov_b32_e32 v116, v0
	v_mov_b32_e32 v117, v0
	v_mov_b32_e32 v118, v0
	v_mov_b32_e32 v119, v0
	v_mov_b32_e32 v72, v0
	v_mov_b32_e32 v73, v0
	v_mov_b32_e32 v74, v0
	v_mov_b32_e32 v75, v0
	v_mov_b32_e32 v76, v0
	v_mov_b32_e32 v77, v0
	v_mov_b32_e32 v78, v0
	v_mov_b32_e32 v79, v0
	v_mov_b32_e32 v88, v0
	v_mov_b32_e32 v89, v0
	v_mov_b32_e32 v90, v0
	v_mov_b32_e32 v91, v0
	v_mov_b32_e32 v92, v0
	v_mov_b32_e32 v93, v0
	v_mov_b32_e32 v94, v0
	v_mov_b32_e32 v95, v0
	v_mov_b32_e32 v104, v0
	v_mov_b32_e32 v105, v0
	v_mov_b32_e32 v106, v0
	v_mov_b32_e32 v107, v0
	v_mov_b32_e32 v108, v0
	v_mov_b32_e32 v109, v0
	v_mov_b32_e32 v110, v0
	v_mov_b32_e32 v111, v0
	v_mov_b32_e32 v120, v0
	v_mov_b32_e32 v121, v0
	v_mov_b32_e32 v122, v0
	v_mov_b32_e32 v123, v0
	v_mov_b32_e32 v124, v0
	v_mov_b32_e32 v125, v0
	v_mov_b32_e32 v126, v0
	v_mov_b32_e32 v127, v0
	.p2align 6

.LBB0_213:
	s_or_b64 exec, exec, s[22:23]
	s_xor_b64 s[22:23], s[10:11], -1
	s_add_i32 s10, 0, 0x10000
	v_lshl_add_u32 v192, v0, 2, s10
	v_cmp_eq_u32_e64 s[10:11], 0, v0
	v_add_u32_e32 v230, s39, v0
	v_mad_i64_i32 v[0:1], s[26:27], v1, s67, 0
	v_lshl_or_b32 v0, v2, 4, v0
	v_mov_b32_e32 v14, v129
	v_mov_b32_e32 v15, v129
	s_lshl_b32 s44, s28, 1
	v_lshl_add_u64 v[180:181], s[20:21], 0, v[0:1]
	v_mov_b32_e32 v0, v129
	v_mov_b32_e32 v1, v129
	v_mov_b32_e32 v2, v129
	v_mov_b32_e32 v3, v129
	v_mov_b32_e32 v4, v129
	s_waitcnt lgkmcnt(0)
	v_mov_b32_e32 v5, v129
	v_mov_b32_e32 v6, v129
	v_mov_b32_e32 v7, v129
	v_mov_b32_e32 v8, v129
	v_mov_b32_e32 v9, v129
	v_mov_b32_e32 v10, v129
	v_mov_b32_e32 v11, v129
	v_mov_b32_e32 v12, v129
	v_mov_b32_e32 v13, v129
	v_mov_b64_e32 v[30:31], v[14:15]
	v_mov_b64_e32 v[46:47], v[14:15]
	v_mov_b64_e32 v[62:63], v[14:15]
	s_add_i32 s44, s44, 2
	s_or_b32 s45, s42, 31
	s_lshl_b32 s46, s41, 3
	s_mov_b32 s47, 0
	v_and_b32_e32 v221, 31, v183
	v_lshrrev_b32_e32 v222, 5, v183
	v_and_b32_e32 v223, 3, v183
	v_lshlrev_b32_e32 v223, 2, v223
	v_bfe_u32 v224, v183, 2, 2
	v_or_b32_e32 v223, v223, v224
	v_add_u32_e32 v225, s46, v222
	v_lshlrev_b32_e32 v226, 8, v221
	v_xor_b32_e32 v227, v225, v223
	v_lshl_add_u32 v209, v227, 4, v226
	v_add_u32_e32 v227, 2, v225
	v_xor_b32_e32 v227, v227, v223
	v_lshl_add_u32 v210, v227, 4, v226
	v_add_u32_e32 v227, 4, v225
	v_xor_b32_e32 v227, v227, v223
	v_lshl_add_u32 v211, v227, 4, v226
	v_add_u32_e32 v227, 6, v225
	v_xor_b32_e32 v227, v227, v223
	v_lshl_add_u32 v212, v227, 4, v226
	v_lshrrev_b32_e32 v227, 3, v183
	v_bfe_u32 v228, v183, 1, 1
	v_and_or_b32 v227, v227, 2, v228
	v_and_b32_e32 v228, 1, v183
	v_lshlrev_b32_e32 v228, 3, v228
	v_lshl_or_b32 v229, v222, 2, v224
	v_lshl_add_u32 v228, v229, 8, v228
	v_xor_b32_e32 v229, v227, v222
	v_lshl_add_u32 v229, v229, 4, v228
	v_lshl_add_u32 v213, v224, 6, v229
	v_xor_b32_e32 v193, 1, v224
	v_lshl_add_u32 v215, v193, 6, v229
	v_xor_b32_e32 v193, 2, v224
	v_lshl_add_u32 v217, v193, 6, v229
	v_xor_b32_e32 v193, 3, v224
	v_lshl_add_u32 v219, v193, 6, v229
	v_add_u32_e32 v229, 2, v222
	v_xor_b32_e32 v229, v227, v229
	v_lshl_add_u32 v229, v229, 4, v228
	v_add_u32_e32 v229, 0x800, v229
	v_lshl_add_u32 v214, v224, 6, v229
	v_xor_b32_e32 v193, 1, v224
	v_lshl_add_u32 v216, v193, 6, v229
	v_xor_b32_e32 v193, 2, v224
	v_lshl_add_u32 v218, v193, 6, v229
	v_xor_b32_e32 v193, 3, v224
	v_lshl_add_u32 v220, v193, 6, v229
	s_addk_i32 s48, 0x80
	v_mov_b32_e32 v232, 0
	v_mov_b32_e32 v235, 0xf149f2ca
	v_mov_b64_e32 v[28:29], v[12:13]
	v_mov_b64_e32 v[26:27], v[10:11]
	v_mov_b64_e32 v[24:25], v[8:9]
	v_mov_b64_e32 v[22:23], v[6:7]
	v_mov_b64_e32 v[20:21], v[4:5]
	v_mov_b64_e32 v[18:19], v[2:3]
	v_mov_b64_e32 v[16:17], v[0:1]
	v_mov_b64_e32 v[44:45], v[12:13]
	v_mov_b64_e32 v[42:43], v[10:11]
	v_mov_b64_e32 v[40:41], v[8:9]
	v_mov_b64_e32 v[38:39], v[6:7]
	v_mov_b64_e32 v[36:37], v[4:5]
	v_mov_b64_e32 v[34:35], v[2:3]
	v_mov_b64_e32 v[32:33], v[0:1]
	v_mov_b64_e32 v[60:61], v[12:13]
	v_mov_b64_e32 v[58:59], v[10:11]
	v_mov_b64_e32 v[56:57], v[8:9]
	v_mov_b64_e32 v[54:55], v[6:7]
	v_mov_b64_e32 v[52:53], v[4:5]
	v_mov_b64_e32 v[50:51], v[2:3]
	v_mov_b64_e32 v[48:49], v[0:1]
	s_mov_b32 s28, 0
	s_barrier
	.p2align 6

.Lgla_st_join_1:
	v_lshlrev_b32_e32 v184, 16, v120
	v_and_b32_e32 v185, s69, v120
	v_lshlrev_b32_e32 v186, 16, v121
	v_and_b32_e32 v187, s69, v121
	v_lshlrev_b32_e32 v188, 16, v124
	v_and_b32_e32 v189, s69, v124
	ds_write_b128 v139, v[180:183] offset:8192
	ds_write_b128 v139, v[184:187] offset:16384
	ds_write2_b32 v140, v188, v189 offset1:4
	global_load_dwordx2 v[126:127], v130, s[8:9]
	global_load_dwordx2 v[190:191], v130, s[8:9] offset:1024
	global_load_dword v119, v131, s[8:9]
	s_add_u32 s8, s8, 0x34000
	s_addc_u32 s9, s9, 0
	global_load_dword v152, v131, s[8:9]
	global_load_dword v152, v131, s[8:9]
	global_load_dwordx2 v[120:121], v130, s[8:9]
	global_load_dwordx2 v[122:123], v130, s[8:9] offset:1024
	global_load_dword v124, v131, s[8:9]
	s_add_u32 s8, s8, 0x34000
	s_addc_u32 s9, s9, 0
	global_load_dword v152, v131, s[8:9]
	global_load_dword v152, v131, s[8:9]
	s_waitcnt lgkmcnt(0)
	s_barrier
	s_cmp_eq_u32 s14, 0
	s_cbranch_scc1 .Lgla_loop_ret
	.p2align 6

.Lgla_st_join_3:
	v_lshlrev_b32_e32 v184, 16, v120
	v_and_b32_e32 v185, s69, v120
	v_lshlrev_b32_e32 v186, 16, v121
	v_and_b32_e32 v187, s69, v121
	v_lshlrev_b32_e32 v188, 16, v124
	v_and_b32_e32 v189, s69, v124
	ds_write_b128 v139, v[180:183] offset:8192
	ds_write_b128 v139, v[184:187] offset:16384
	ds_write2_b32 v140, v188, v189 offset1:4
	global_load_dwordx2 v[120:121], v130, s[8:9]
	global_load_dwordx2 v[122:123], v130, s[8:9] offset:1024
	global_load_dword v124, v131, s[8:9]
	s_add_u32 s8, s8, 0x34000
	s_addc_u32 s9, s9, 0
	s_waitcnt lgkmcnt(3)
	v_add_f32_e32 v112, v104, v105
	v_add_f32_e32 v112, v112, v106
	v_add_f32_e32 v112, v112, v107
	v_add_f32_e32 v112, v112, v108
	v_add_f32_e32 v112, v112, v109
	v_add_f32_e32 v112, v112, v110
	v_add_f32_e32 v112, v112, v111
	v_mul_f32_e32 v113, v112, v112
	v_cvt_pk_bf16_f32 v116, v112, v129
	v_mov_b32_e32 v117, v112
	v_mov_b32_e32 v118, v113
	global_store_short v132, v116, s[10:11]
	s_nop 1
	v_permlane16_swap_b32_e32 v112, v117
	v_permlane16_swap_b32_e32 v113, v118
	v_add_f32_e32 v112, v112, v117
	v_add_f32_e32 v113, v113, v118
	s_nop 1
	v_add_f32_dpp v112, v112, v112 row_ror:8 row_mask:0xf bank_mask:0xf
	v_add_f32_dpp v113, v113, v113 row_ror:8 row_mask:0xf bank_mask:0xf
	s_nop 1
	v_add_f32_dpp v112, v112, v112 row_ror:4 row_mask:0xf bank_mask:0xf
	v_add_f32_dpp v113, v113, v113 row_ror:4 row_mask:0xf bank_mask:0xf
	s_nop 1
	v_add_f32_dpp v112, v112, v112 row_ror:2 row_mask:0xf bank_mask:0xf
	v_add_f32_dpp v113, v113, v113 row_ror:2 row_mask:0xf bank_mask:0xf
	s_nop 1
	v_add_f32_dpp v112, v112, v112 row_ror:1 row_mask:0xf bank_mask:0xf
	v_add_f32_dpp v113, v113, v113 row_ror:1 row_mask:0xf bank_mask:0xf
	v_mov_b32_e32 v114, 0
	v_mov_b32_e32 v115, 0
	s_mov_b64 exec, s[18:19]
	global_store_dwordx4 v133, v[112:115], s[12:13]
	s_mov_b64 exec, -1
	s_cmp_eq_u32 s15, 512
	s_cselect_b32 s20, 0, 0x10000
	s_cselect_b32 s21, 0, 0x1000
	s_add_u32 s10, s10, s20
	s_addc_u32 s11, s11, 0
	s_add_u32 s12, s12, s21
	s_addc_u32 s13, s13, 0
	ds_read_b128 v[80:83], v135 offset:57344
	ds_read_b128 v[40:43], v134 offset:40960
	ds_read_b128 v[44:47], v134 offset:49152
	ds_read_b128 v[48:51], v134 offset:41472
	ds_read_b128 v[52:55], v134 offset:49664
	ds_read_b128 v[84:87], v135 offset:57600
	ds_read_b128 v[56:59], v134 offset:41984
	ds_read_b128 v[60:63], v134 offset:50176
	ds_read_b128 v[64:67], v134 offset:42496
	ds_read_b128 v[68:71], v134 offset:50688
	s_waitcnt lgkmcnt(7)
	v_pk_add_f32 v[92:93], v[0:1], v[80:81] neg_lo:[0,1] neg_hi:[0,1]
	v_pk_add_f32 v[94:95], v[2:3], v[80:81] neg_lo:[0,1] neg_hi:[0,1]
	v_pk_add_f32 v[96:97], v[4:5], v[80:81] neg_lo:[0,1] neg_hi:[0,1]
	v_pk_add_f32 v[98:99], v[6:7], v[80:81] neg_lo:[0,1] neg_hi:[0,1]
	v_pk_fma_f32 v[0:1], v[92:93], v[40:41], v[80:81] op_sel_hi:[1,0,1]
	v_pk_fma_f32 v[2:3], v[94:95], v[40:41], v[80:81] op_sel:[0,1,0] op_sel_hi:[1,1,1]
	v_pk_fma_f32 v[4:5], v[96:97], v[42:43], v[80:81] op_sel_hi:[1,0,1]
	v_pk_fma_f32 v[6:7], v[98:99], v[42:43], v[80:81] op_sel:[0,1,0] op_sel_hi:[1,1,1]
	ds_read_b128 v[88:91], v135 offset:57856
	ds_read_b128 v[72:75], v134 offset:43008
	ds_read_b128 v[76:79], v134 offset:51200
	s_waitcnt lgkmcnt(8)
	v_pk_add_f32 v[92:93], v[0:1], v[82:83] neg_lo:[0,1] neg_hi:[0,1]
	v_pk_mul_f32 v[8:9], v[0:1], v[44:45] op_sel_hi:[1,0]
	v_pk_add_f32 v[94:95], v[2:3], v[82:83] neg_lo:[0,1] neg_hi:[0,1]
	v_pk_fma_f32 v[8:9], v[2:3], v[44:45], v[8:9] op_sel:[0,1,0] op_sel_hi:[1,1,1]
	v_pk_add_f32 v[96:97], v[4:5], v[82:83] neg_lo:[0,1] neg_hi:[0,1]
	v_pk_fma_f32 v[8:9], v[4:5], v[46:47], v[8:9] op_sel_hi:[1,0,1]
	v_pk_add_f32 v[98:99], v[6:7], v[82:83] neg_lo:[0,1] neg_hi:[0,1]
	v_pk_fma_f32 v[8:9], v[6:7], v[46:47], v[8:9] op_sel:[0,1,0] op_sel_hi:[1,1,1]
	v_pk_fma_f32 v[0:1], v[92:93], v[48:49], v[82:83] op_sel_hi:[1,0,1]
	v_pk_fma_f32 v[2:3], v[94:95], v[48:49], v[82:83] op_sel:[0,1,0] op_sel_hi:[1,1,1]
	v_pk_fma_f32 v[4:5], v[96:97], v[50:51], v[82:83] op_sel_hi:[1,0,1]
	v_pk_fma_f32 v[6:7], v[98:99], v[50:51], v[82:83] op_sel:[0,1,0] op_sel_hi:[1,1,1]
	ds_read_b128 v[40:43], v134 offset:43520
	ds_read_b128 v[44:47], v134 offset:51712
	s_waitcnt lgkmcnt(7)
	v_pk_add_f32 v[92:93], v[0:1], v[84:85] neg_lo:[0,1] neg_hi:[0,1]
	v_pk_mul_f32 v[10:11], v[0:1], v[52:53] op_sel_hi:[1,0]
	v_pk_add_f32 v[94:95], v[2:3], v[84:85] neg_lo:[0,1] neg_hi:[0,1]
	v_pk_fma_f32 v[10:11], v[2:3], v[52:53], v[10:11] op_sel:[0,1,0] op_sel_hi:[1,1,1]
	v_pk_add_f32 v[96:97], v[4:5], v[84:85] neg_lo:[0,1] neg_hi:[0,1]
	v_pk_fma_f32 v[10:11], v[4:5], v[54:55], v[10:11] op_sel_hi:[1,0,1]
	v_pk_add_f32 v[98:99], v[6:7], v[84:85] neg_lo:[0,1] neg_hi:[0,1]
	v_pk_fma_f32 v[10:11], v[6:7], v[54:55], v[10:11] op_sel:[0,1,0] op_sel_hi:[1,1,1]
	v_pk_fma_f32 v[0:1], v[92:93], v[56:57], v[84:85] op_sel_hi:[1,0,1]
	v_pk_fma_f32 v[2:3], v[94:95], v[56:57], v[84:85] op_sel:[0,1,0] op_sel_hi:[1,1,1]
	v_pk_fma_f32 v[4:5], v[96:97], v[58:59], v[84:85] op_sel_hi:[1,0,1]
	v_pk_fma_f32 v[6:7], v[98:99], v[58:59], v[84:85] op_sel:[0,1,0] op_sel_hi:[1,1,1]
	ds_read_b128 v[80:83], v135 offset:58112
	ds_read_b128 v[48:51], v134 offset:44032
	ds_read_b128 v[52:55], v134 offset:52224
	s_waitcnt lgkmcnt(8)
	v_pk_add_f32 v[92:93], v[0:1], v[86:87] neg_lo:[0,1] neg_hi:[0,1]
	v_pk_mul_f32 v[12:13], v[0:1], v[60:61] op_sel_hi:[1,0]
	v_pk_add_f32 v[94:95], v[2:3], v[86:87] neg_lo:[0,1] neg_hi:[0,1]
	v_pk_fma_f32 v[12:13], v[2:3], v[60:61], v[12:13] op_sel:[0,1,0] op_sel_hi:[1,1,1]
	v_pk_add_f32 v[96:97], v[4:5], v[86:87] neg_lo:[0,1] neg_hi:[0,1]
	v_pk_fma_f32 v[12:13], v[4:5], v[62:63], v[12:13] op_sel_hi:[1,0,1]
	v_pk_add_f32 v[98:99], v[6:7], v[86:87] neg_lo:[0,1] neg_hi:[0,1]
	v_pk_fma_f32 v[12:13], v[6:7], v[62:63], v[12:13] op_sel:[0,1,0] op_sel_hi:[1,1,1]
	v_pk_fma_f32 v[0:1], v[92:93], v[64:65], v[86:87] op_sel_hi:[1,0,1]
	v_pk_fma_f32 v[2:3], v[94:95], v[64:65], v[86:87] op_sel:[0,1,0] op_sel_hi:[1,1,1]
	v_pk_fma_f32 v[4:5], v[96:97], v[66:67], v[86:87] op_sel_hi:[1,0,1]
	v_pk_fma_f32 v[6:7], v[98:99], v[66:67], v[86:87] op_sel:[0,1,0] op_sel_hi:[1,1,1]
	ds_read_b128 v[56:59], v134 offset:44544
	ds_read_b128 v[60:63], v134 offset:52736
	s_waitcnt lgkmcnt(7)
	v_pk_add_f32 v[92:93], v[0:1], v[88:89] neg_lo:[0,1] neg_hi:[0,1]
	v_pk_mul_f32 v[14:15], v[0:1], v[68:69] op_sel_hi:[1,0]
	v_pk_add_f32 v[94:95], v[2:3], v[88:89] neg_lo:[0,1] neg_hi:[0,1]
	v_pk_fma_f32 v[14:15], v[2:3], v[68:69], v[14:15] op_sel:[0,1,0] op_sel_hi:[1,1,1]
	v_pk_add_f32 v[96:97], v[4:5], v[88:89] neg_lo:[0,1] neg_hi:[0,1]
	v_pk_fma_f32 v[14:15], v[4:5], v[70:71], v[14:15] op_sel_hi:[1,0,1]
	v_pk_add_f32 v[98:99], v[6:7], v[88:89] neg_lo:[0,1] neg_hi:[0,1]
	v_pk_fma_f32 v[14:15], v[6:7], v[70:71], v[14:15] op_sel:[0,1,0] op_sel_hi:[1,1,1]
	v_pk_fma_f32 v[0:1], v[92:93], v[72:73], v[88:89] op_sel_hi:[1,0,1]
	v_pk_fma_f32 v[2:3], v[94:95], v[72:73], v[88:89] op_sel:[0,1,0] op_sel_hi:[1,1,1]
	v_pk_fma_f32 v[4:5], v[96:97], v[74:75], v[88:89] op_sel_hi:[1,0,1]
	v_pk_fma_f32 v[6:7], v[98:99], v[74:75], v[88:89] op_sel:[0,1,0] op_sel_hi:[1,1,1]
	ds_read_b128 v[84:87], v135 offset:58368
	ds_read_b128 v[64:67], v134 offset:45056
	ds_read_b128 v[68:71], v134 offset:53248
	s_waitcnt lgkmcnt(8)
	v_pk_add_f32 v[92:93], v[0:1], v[90:91] neg_lo:[0,1] neg_hi:[0,1]
	v_pk_mul_f32 v[16:17], v[0:1], v[76:77] op_sel_hi:[1,0]
	v_pk_add_f32 v[94:95], v[2:3], v[90:91] neg_lo:[0,1] neg_hi:[0,1]
	v_pk_fma_f32 v[16:17], v[2:3], v[76:77], v[16:17] op_sel:[0,1,0] op_sel_hi:[1,1,1]
	v_pk_add_f32 v[96:97], v[4:5], v[90:91] neg_lo:[0,1] neg_hi:[0,1]
	v_pk_fma_f32 v[16:17], v[4:5], v[78:79], v[16:17] op_sel_hi:[1,0,1]
	v_pk_add_f32 v[98:99], v[6:7], v[90:91] neg_lo:[0,1] neg_hi:[0,1]
	v_pk_fma_f32 v[16:17], v[6:7], v[78:79], v[16:17] op_sel:[0,1,0] op_sel_hi:[1,1,1]
	v_pk_fma_f32 v[0:1], v[92:93], v[40:41], v[90:91] op_sel_hi:[1,0,1]
	v_pk_fma_f32 v[2:3], v[94:95], v[40:41], v[90:91] op_sel:[0,1,0] op_sel_hi:[1,1,1]
	v_pk_fma_f32 v[4:5], v[96:97], v[42:43], v[90:91] op_sel_hi:[1,0,1]
	v_pk_fma_f32 v[6:7], v[98:99], v[42:43], v[90:91] op_sel:[0,1,0] op_sel_hi:[1,1,1]
	ds_read_b128 v[72:75], v134 offset:45568
	ds_read_b128 v[76:79], v134 offset:53760
	s_waitcnt lgkmcnt(7)
	v_pk_add_f32 v[92:93], v[0:1], v[80:81] neg_lo:[0,1] neg_hi:[0,1]
	v_pk_mul_f32 v[18:19], v[0:1], v[44:45] op_sel_hi:[1,0]
	v_pk_add_f32 v[94:95], v[2:3], v[80:81] neg_lo:[0,1] neg_hi:[0,1]
	v_pk_fma_f32 v[18:19], v[2:3], v[44:45], v[18:19] op_sel:[0,1,0] op_sel_hi:[1,1,1]
	v_pk_add_f32 v[96:97], v[4:5], v[80:81] neg_lo:[0,1] neg_hi:[0,1]
	v_pk_fma_f32 v[18:19], v[4:5], v[46:47], v[18:19] op_sel_hi:[1,0,1]
	v_pk_add_f32 v[98:99], v[6:7], v[80:81] neg_lo:[0,1] neg_hi:[0,1]
	v_pk_fma_f32 v[18:19], v[6:7], v[46:47], v[18:19] op_sel:[0,1,0] op_sel_hi:[1,1,1]
	v_pk_fma_f32 v[0:1], v[92:93], v[48:49], v[80:81] op_sel_hi:[1,0,1]
	v_pk_fma_f32 v[2:3], v[94:95], v[48:49], v[80:81] op_sel:[0,1,0] op_sel_hi:[1,1,1]
	v_pk_fma_f32 v[4:5], v[96:97], v[50:51], v[80:81] op_sel_hi:[1,0,1]
	v_pk_fma_f32 v[6:7], v[98:99], v[50:51], v[80:81] op_sel:[0,1,0] op_sel_hi:[1,1,1]
	ds_read_b128 v[88:91], v135 offset:58624
	ds_read_b128 v[40:43], v134 offset:46080
	ds_read_b128 v[44:47], v134 offset:54272
	s_waitcnt lgkmcnt(8)
	v_pk_add_f32 v[92:93], v[0:1], v[82:83] neg_lo:[0,1] neg_hi:[0,1]
	v_pk_mul_f32 v[20:21], v[0:1], v[52:53] op_sel_hi:[1,0]
	v_pk_add_f32 v[94:95], v[2:3], v[82:83] neg_lo:[0,1] neg_hi:[0,1]
	v_pk_fma_f32 v[20:21], v[2:3], v[52:53], v[20:21] op_sel:[0,1,0] op_sel_hi:[1,1,1]
	v_pk_add_f32 v[96:97], v[4:5], v[82:83] neg_lo:[0,1] neg_hi:[0,1]
	v_pk_fma_f32 v[20:21], v[4:5], v[54:55], v[20:21] op_sel_hi:[1,0,1]
	v_pk_add_f32 v[98:99], v[6:7], v[82:83] neg_lo:[0,1] neg_hi:[0,1]
	v_pk_fma_f32 v[20:21], v[6:7], v[54:55], v[20:21] op_sel:[0,1,0] op_sel_hi:[1,1,1]
	v_pk_fma_f32 v[0:1], v[92:93], v[56:57], v[82:83] op_sel_hi:[1,0,1]
	v_pk_fma_f32 v[2:3], v[94:95], v[56:57], v[82:83] op_sel:[0,1,0] op_sel_hi:[1,1,1]
	v_pk_fma_f32 v[4:5], v[96:97], v[58:59], v[82:83] op_sel_hi:[1,0,1]
	v_pk_fma_f32 v[6:7], v[98:99], v[58:59], v[82:83] op_sel:[0,1,0] op_sel_hi:[1,1,1]
	ds_read_b128 v[48:51], v134 offset:46592
	ds_read_b128 v[52:55], v134 offset:54784
	s_waitcnt lgkmcnt(7)
	v_pk_add_f32 v[92:93], v[0:1], v[84:85] neg_lo:[0,1] neg_hi:[0,1]
	v_pk_mul_f32 v[22:23], v[0:1], v[60:61] op_sel_hi:[1,0]
	v_pk_add_f32 v[94:95], v[2:3], v[84:85] neg_lo:[0,1] neg_hi:[0,1]
	v_pk_fma_f32 v[22:23], v[2:3], v[60:61], v[22:23] op_sel:[0,1,0] op_sel_hi:[1,1,1]
	v_pk_add_f32 v[96:97], v[4:5], v[84:85] neg_lo:[0,1] neg_hi:[0,1]
	v_pk_fma_f32 v[22:23], v[4:5], v[62:63], v[22:23] op_sel_hi:[1,0,1]
	v_pk_add_f32 v[98:99], v[6:7], v[84:85] neg_lo:[0,1] neg_hi:[0,1]
	v_pk_fma_f32 v[22:23], v[6:7], v[62:63], v[22:23] op_sel:[0,1,0] op_sel_hi:[1,1,1]
	v_pk_fma_f32 v[0:1], v[92:93], v[64:65], v[84:85] op_sel_hi:[1,0,1]
	v_pk_fma_f32 v[2:3], v[94:95], v[64:65], v[84:85] op_sel:[0,1,0] op_sel_hi:[1,1,1]
	v_pk_fma_f32 v[4:5], v[96:97], v[66:67], v[84:85] op_sel_hi:[1,0,1]
	v_pk_fma_f32 v[6:7], v[98:99], v[66:67], v[84:85] op_sel:[0,1,0] op_sel_hi:[1,1,1]
	ds_read_b128 v[80:83], v135 offset:58880
	ds_read_b128 v[56:59], v134 offset:47104
	ds_read_b128 v[60:63], v134 offset:55296
	s_waitcnt lgkmcnt(8)
	v_pk_add_f32 v[92:93], v[0:1], v[86:87] neg_lo:[0,1] neg_hi:[0,1]
	v_pk_mul_f32 v[24:25], v[0:1], v[68:69] op_sel_hi:[1,0]
	v_pk_add_f32 v[94:95], v[2:3], v[86:87] neg_lo:[0,1] neg_hi:[0,1]
	v_pk_fma_f32 v[24:25], v[2:3], v[68:69], v[24:25] op_sel:[0,1,0] op_sel_hi:[1,1,1]
	v_pk_add_f32 v[96:97], v[4:5], v[86:87] neg_lo:[0,1] neg_hi:[0,1]
	v_pk_fma_f32 v[24:25], v[4:5], v[70:71], v[24:25] op_sel_hi:[1,0,1]
	v_pk_add_f32 v[98:99], v[6:7], v[86:87] neg_lo:[0,1] neg_hi:[0,1]
	v_pk_fma_f32 v[24:25], v[6:7], v[70:71], v[24:25] op_sel:[0,1,0] op_sel_hi:[1,1,1]
	v_pk_fma_f32 v[0:1], v[92:93], v[72:73], v[86:87] op_sel_hi:[1,0,1]
	v_pk_fma_f32 v[2:3], v[94:95], v[72:73], v[86:87] op_sel:[0,1,0] op_sel_hi:[1,1,1]
	v_pk_fma_f32 v[4:5], v[96:97], v[74:75], v[86:87] op_sel_hi:[1,0,1]
	v_pk_fma_f32 v[6:7], v[98:99], v[74:75], v[86:87] op_sel:[0,1,0] op_sel_hi:[1,1,1]
	ds_read_b128 v[64:67], v134 offset:47616
	ds_read_b128 v[68:71], v134 offset:55808
	s_waitcnt lgkmcnt(7)
	v_pk_add_f32 v[92:93], v[0:1], v[88:89] neg_lo:[0,1] neg_hi:[0,1]
	v_pk_mul_f32 v[26:27], v[0:1], v[76:77] op_sel_hi:[1,0]
	v_pk_add_f32 v[94:95], v[2:3], v[88:89] neg_lo:[0,1] neg_hi:[0,1]
	v_pk_fma_f32 v[26:27], v[2:3], v[76:77], v[26:27] op_sel:[0,1,0] op_sel_hi:[1,1,1]
	v_pk_add_f32 v[96:97], v[4:5], v[88:89] neg_lo:[0,1] neg_hi:[0,1]
	v_pk_fma_f32 v[26:27], v[4:5], v[78:79], v[26:27] op_sel_hi:[1,0,1]
	v_pk_add_f32 v[98:99], v[6:7], v[88:89] neg_lo:[0,1] neg_hi:[0,1]
	v_pk_fma_f32 v[26:27], v[6:7], v[78:79], v[26:27] op_sel:[0,1,0] op_sel_hi:[1,1,1]
	v_pk_fma_f32 v[0:1], v[92:93], v[40:41], v[88:89] op_sel_hi:[1,0,1]
	v_pk_fma_f32 v[2:3], v[94:95], v[40:41], v[88:89] op_sel:[0,1,0] op_sel_hi:[1,1,1]
	v_pk_fma_f32 v[4:5], v[96:97], v[42:43], v[88:89] op_sel_hi:[1,0,1]
	v_pk_fma_f32 v[6:7], v[98:99], v[42:43], v[88:89] op_sel:[0,1,0] op_sel_hi:[1,1,1]
	ds_read_b128 v[84:87], v135 offset:59136
	ds_read_b128 v[72:75], v134 offset:48128
	ds_read_b128 v[76:79], v134 offset:56320
	s_waitcnt lgkmcnt(8)
	v_pk_add_f32 v[92:93], v[0:1], v[90:91] neg_lo:[0,1] neg_hi:[0,1]
	v_pk_mul_f32 v[28:29], v[0:1], v[44:45] op_sel_hi:[1,0]
	v_pk_add_f32 v[94:95], v[2:3], v[90:91] neg_lo:[0,1] neg_hi:[0,1]
	v_pk_fma_f32 v[28:29], v[2:3], v[44:45], v[28:29] op_sel:[0,1,0] op_sel_hi:[1,1,1]
	v_pk_add_f32 v[96:97], v[4:5], v[90:91] neg_lo:[0,1] neg_hi:[0,1]
	v_pk_fma_f32 v[28:29], v[4:5], v[46:47], v[28:29] op_sel_hi:[1,0,1]
	v_pk_add_f32 v[98:99], v[6:7], v[90:91] neg_lo:[0,1] neg_hi:[0,1]
	v_pk_fma_f32 v[28:29], v[6:7], v[46:47], v[28:29] op_sel:[0,1,0] op_sel_hi:[1,1,1]
	v_pk_fma_f32 v[0:1], v[92:93], v[48:49], v[90:91] op_sel_hi:[1,0,1]
	v_pk_fma_f32 v[2:3], v[94:95], v[48:49], v[90:91] op_sel:[0,1,0] op_sel_hi:[1,1,1]
	v_pk_fma_f32 v[4:5], v[96:97], v[50:51], v[90:91] op_sel_hi:[1,0,1]
	v_pk_fma_f32 v[6:7], v[98:99], v[50:51], v[90:91] op_sel:[0,1,0] op_sel_hi:[1,1,1]
	ds_read_b128 v[40:43], v134 offset:48640
	ds_read_b128 v[44:47], v134 offset:56832
	s_waitcnt lgkmcnt(7)
	v_pk_add_f32 v[92:93], v[0:1], v[80:81] neg_lo:[0,1] neg_hi:[0,1]
	v_pk_mul_f32 v[30:31], v[0:1], v[52:53] op_sel_hi:[1,0]
	v_pk_add_f32 v[94:95], v[2:3], v[80:81] neg_lo:[0,1] neg_hi:[0,1]
	v_pk_fma_f32 v[30:31], v[2:3], v[52:53], v[30:31] op_sel:[0,1,0] op_sel_hi:[1,1,1]
	v_pk_add_f32 v[96:97], v[4:5], v[80:81] neg_lo:[0,1] neg_hi:[0,1]
	v_pk_fma_f32 v[30:31], v[4:5], v[54:55], v[30:31] op_sel_hi:[1,0,1]
	v_pk_add_f32 v[98:99], v[6:7], v[80:81] neg_lo:[0,1] neg_hi:[0,1]
	v_pk_fma_f32 v[30:31], v[6:7], v[54:55], v[30:31] op_sel:[0,1,0] op_sel_hi:[1,1,1]
	v_pk_fma_f32 v[0:1], v[92:93], v[56:57], v[80:81] op_sel_hi:[1,0,1]
	v_pk_fma_f32 v[2:3], v[94:95], v[56:57], v[80:81] op_sel:[0,1,0] op_sel_hi:[1,1,1]
	v_pk_fma_f32 v[4:5], v[96:97], v[58:59], v[80:81] op_sel_hi:[1,0,1]
	v_pk_fma_f32 v[6:7], v[98:99], v[58:59], v[80:81] op_sel:[0,1,0] op_sel_hi:[1,1,1]
	s_waitcnt lgkmcnt(5)
	v_pk_add_f32 v[92:93], v[0:1], v[82:83] neg_lo:[0,1] neg_hi:[0,1]
	v_pk_mul_f32 v[32:33], v[0:1], v[60:61] op_sel_hi:[1,0]
	v_pk_add_f32 v[94:95], v[2:3], v[82:83] neg_lo:[0,1] neg_hi:[0,1]
	v_pk_fma_f32 v[32:33], v[2:3], v[60:61], v[32:33] op_sel:[0,1,0] op_sel_hi:[1,1,1]
	v_pk_add_f32 v[96:97], v[4:5], v[82:83] neg_lo:[0,1] neg_hi:[0,1]
	v_pk_fma_f32 v[32:33], v[4:5], v[62:63], v[32:33] op_sel_hi:[1,0,1]
	v_pk_add_f32 v[98:99], v[6:7], v[82:83] neg_lo:[0,1] neg_hi:[0,1]
	v_pk_fma_f32 v[32:33], v[6:7], v[62:63], v[32:33] op_sel:[0,1,0] op_sel_hi:[1,1,1]
	v_pk_fma_f32 v[0:1], v[92:93], v[64:65], v[82:83] op_sel_hi:[1,0,1]
	v_pk_fma_f32 v[2:3], v[94:95], v[64:65], v[82:83] op_sel:[0,1,0] op_sel_hi:[1,1,1]
	v_pk_fma_f32 v[4:5], v[96:97], v[66:67], v[82:83] op_sel_hi:[1,0,1]
	v_pk_fma_f32 v[6:7], v[98:99], v[66:67], v[82:83] op_sel:[0,1,0] op_sel_hi:[1,1,1]
	s_waitcnt lgkmcnt(2)
	v_pk_add_f32 v[92:93], v[0:1], v[84:85] neg_lo:[0,1] neg_hi:[0,1]
	v_pk_mul_f32 v[34:35], v[0:1], v[68:69] op_sel_hi:[1,0]
	v_pk_add_f32 v[94:95], v[2:3], v[84:85] neg_lo:[0,1] neg_hi:[0,1]
	v_pk_fma_f32 v[34:35], v[2:3], v[68:69], v[34:35] op_sel:[0,1,0] op_sel_hi:[1,1,1]
	v_pk_add_f32 v[96:97], v[4:5], v[84:85] neg_lo:[0,1] neg_hi:[0,1]
	v_pk_fma_f32 v[34:35], v[4:5], v[70:71], v[34:35] op_sel_hi:[1,0,1]
	v_pk_add_f32 v[98:99], v[6:7], v[84:85] neg_lo:[0,1] neg_hi:[0,1]
	v_pk_fma_f32 v[34:35], v[6:7], v[70:71], v[34:35] op_sel:[0,1,0] op_sel_hi:[1,1,1]
	v_pk_fma_f32 v[0:1], v[92:93], v[72:73], v[84:85] op_sel_hi:[1,0,1]
	v_pk_fma_f32 v[2:3], v[94:95], v[72:73], v[84:85] op_sel:[0,1,0] op_sel_hi:[1,1,1]
	v_pk_fma_f32 v[4:5], v[96:97], v[74:75], v[84:85] op_sel_hi:[1,0,1]
	v_pk_fma_f32 v[6:7], v[98:99], v[74:75], v[84:85] op_sel:[0,1,0] op_sel_hi:[1,1,1]
	s_waitcnt lgkmcnt(0)
	v_pk_add_f32 v[92:93], v[0:1], v[86:87] neg_lo:[0,1] neg_hi:[0,1]
	v_pk_mul_f32 v[36:37], v[0:1], v[76:77] op_sel_hi:[1,0]
	v_pk_add_f32 v[94:95], v[2:3], v[86:87] neg_lo:[0,1] neg_hi:[0,1]
	v_pk_fma_f32 v[36:37], v[2:3], v[76:77], v[36:37] op_sel:[0,1,0] op_sel_hi:[1,1,1]
	v_pk_add_f32 v[96:97], v[4:5], v[86:87] neg_lo:[0,1] neg_hi:[0,1]
	v_pk_fma_f32 v[36:37], v[4:5], v[78:79], v[36:37] op_sel_hi:[1,0,1]
	v_pk_add_f32 v[98:99], v[6:7], v[86:87] neg_lo:[0,1] neg_hi:[0,1]
	v_pk_fma_f32 v[36:37], v[6:7], v[78:79], v[36:37] op_sel:[0,1,0] op_sel_hi:[1,1,1]
	v_pk_fma_f32 v[0:1], v[92:93], v[40:41], v[86:87] op_sel_hi:[1,0,1]
	v_pk_fma_f32 v[2:3], v[94:95], v[40:41], v[86:87] op_sel:[0,1,0] op_sel_hi:[1,1,1]
	v_pk_fma_f32 v[4:5], v[96:97], v[42:43], v[86:87] op_sel_hi:[1,0,1]
	v_pk_fma_f32 v[6:7], v[98:99], v[42:43], v[86:87] op_sel:[0,1,0] op_sel_hi:[1,1,1]
	v_pk_mul_f32 v[38:39], v[0:1], v[44:45] op_sel_hi:[1,0]
	v_pk_fma_f32 v[38:39], v[2:3], v[44:45], v[38:39] op_sel:[0,1,0] op_sel_hi:[1,1,1]
	v_pk_fma_f32 v[38:39], v[4:5], v[46:47], v[38:39] op_sel_hi:[1,0,1]
	v_pk_fma_f32 v[38:39], v[6:7], v[46:47], v[38:39] op_sel:[0,1,0] op_sel_hi:[1,1,1]
	s_nop 1
	v_permlane16_swap_b32_e32 v8, v24
	v_permlane16_swap_b32_e32 v9, v25
	v_permlane16_swap_b32_e32 v10, v26
	v_permlane16_swap_b32_e32 v11, v27
	v_permlane16_swap_b32_e32 v12, v28
	v_permlane16_swap_b32_e32 v13, v29
	v_permlane16_swap_b32_e32 v14, v30
	v_permlane16_swap_b32_e32 v15, v31
	v_permlane16_swap_b32_e32 v16, v32
	v_permlane16_swap_b32_e32 v17, v33
	v_permlane16_swap_b32_e32 v18, v34
	v_permlane16_swap_b32_e32 v19, v35
	v_permlane16_swap_b32_e32 v20, v36
	v_permlane16_swap_b32_e32 v21, v37
	v_permlane16_swap_b32_e32 v22, v38
	v_permlane16_swap_b32_e32 v23, v39
	v_pk_add_f32 v[8:9], v[8:9], v[24:25]
	v_pk_add_f32 v[10:11], v[10:11], v[26:27]
	v_pk_add_f32 v[12:13], v[12:13], v[28:29]
	v_pk_add_f32 v[14:15], v[14:15], v[30:31]
	v_pk_add_f32 v[16:17], v[16:17], v[32:33]
	v_pk_add_f32 v[18:19], v[18:19], v[34:35]
	v_pk_add_f32 v[20:21], v[20:21], v[36:37]
	v_pk_add_f32 v[22:23], v[22:23], v[38:39]
	s_nop 1
	v_permlane32_swap_b32_e32 v8, v16
	v_permlane32_swap_b32_e32 v9, v17
	v_permlane32_swap_b32_e32 v10, v18
	v_permlane32_swap_b32_e32 v11, v19
	v_permlane32_swap_b32_e32 v12, v20
	v_permlane32_swap_b32_e32 v13, v21
	v_permlane32_swap_b32_e32 v14, v22
	v_permlane32_swap_b32_e32 v15, v23
	v_pk_add_f32 v[8:9], v[8:9], v[16:17]
	v_pk_add_f32 v[10:11], v[10:11], v[18:19]
	v_pk_add_f32 v[12:13], v[12:13], v[20:21]
	v_pk_add_f32 v[14:15], v[14:15], v[22:23]
	ds_write2_b32 v145, v8, v9 offset1:16
	ds_write2_b32 v146, v10, v11 offset1:16
	ds_write2_b32 v147, v12, v13 offset1:16
	ds_write2_b32 v148, v14, v15 offset1:16
	s_sub_u32 s15, s15, 1
	s_waitcnt lgkmcnt(0)
	s_barrier
	s_cmp_lg_u32 s15, 0
	s_cbranch_scc1 .Lgla_loop_hgrn
	s_branch .Lgla_tail
	.p2align 6

.LBB0_302:
	s_ashr_i32 s21, s20, 31
	v_cmp_lt_i64_e32 vcc, s[22:23], v[174:175]
	s_lshl_b64 s[0:1], s[20:21], 20
	v_readlane_b32 s22, v255, 34
	v_readlane_b32 s23, v255, 35
	s_add_u32 s22, s22, s0
	s_addc_u32 s23, s23, s1
	s_and_b64 s[0:1], vcc, exec
	s_cselect_b32 s0, s23, s13
	s_cselect_b32 s1, s22, s12
	s_ashr_i32 s19, s18, 31
	s_lshl_b64 s[24:25], s[18:19], 20
	s_add_u32 s24, s36, s24
	s_addc_u32 s25, s37, s25
	s_and_b64 s[30:31], vcc, exec
	s_cselect_b32 s11, s25, s29
	s_cselect_b32 s19, s24, s28
	s_add_u32 s12, s12, 0x80080
	s_addc_u32 s13, s13, 0
	s_add_u32 s21, s28, 0x100
	v_mov_b32_e32 v0, 0
	s_addc_u32 s46, s29, 0
	s_mov_b32 s47, -2
	v_mov_b32_e32 v1, v0
	v_mov_b32_e32 v2, v0
	v_mov_b32_e32 v3, v0
	v_mov_b32_e32 v4, v0
	v_mov_b32_e32 v5, v0
	v_mov_b32_e32 v6, v0
	v_mov_b32_e32 v7, v0
	v_mov_b32_e32 v16, v0
	v_mov_b32_e32 v17, v0
	v_mov_b32_e32 v18, v0
	v_mov_b32_e32 v19, v0
	v_mov_b32_e32 v20, v0
	v_mov_b32_e32 v21, v0
	v_mov_b32_e32 v22, v0
	v_mov_b32_e32 v23, v0
	v_mov_b32_e32 v32, v0
	v_mov_b32_e32 v33, v0
	v_mov_b32_e32 v34, v0
	v_mov_b32_e32 v35, v0
	v_mov_b32_e32 v36, v0
	v_mov_b32_e32 v37, v0
	v_mov_b32_e32 v38, v0
	v_mov_b32_e32 v39, v0
	v_mov_b32_e32 v48, v0
	v_mov_b32_e32 v49, v0
	v_mov_b32_e32 v50, v0
	v_mov_b32_e32 v51, v0
	v_mov_b32_e32 v52, v0
	v_mov_b32_e32 v53, v0
	v_mov_b32_e32 v54, v0
	v_mov_b32_e32 v55, v0
	v_mov_b32_e32 v8, v0
	v_mov_b32_e32 v9, v0
	v_mov_b32_e32 v10, v0
	v_mov_b32_e32 v11, v0
	v_mov_b32_e32 v12, v0
	v_mov_b32_e32 v13, v0
	v_mov_b32_e32 v14, v0
	v_mov_b32_e32 v15, v0
	v_mov_b32_e32 v24, v0
	v_mov_b32_e32 v25, v0
	v_mov_b32_e32 v26, v0
	v_mov_b32_e32 v27, v0
	v_mov_b32_e32 v28, v0
	v_mov_b32_e32 v29, v0
	v_mov_b32_e32 v30, v0
	v_mov_b32_e32 v31, v0
	v_mov_b32_e32 v40, v0
	v_mov_b32_e32 v41, v0
	v_mov_b32_e32 v42, v0
	v_mov_b32_e32 v43, v0
	v_mov_b32_e32 v44, v0
	v_mov_b32_e32 v45, v0
	v_mov_b32_e32 v46, v0
	v_mov_b32_e32 v47, v0
	v_mov_b32_e32 v56, v0
	v_mov_b32_e32 v57, v0
	v_mov_b32_e32 v58, v0
	v_mov_b32_e32 v59, v0
	v_mov_b32_e32 v60, v0
	v_mov_b32_e32 v61, v0
	v_mov_b32_e32 v62, v0
	v_mov_b32_e32 v63, v0
	v_mov_b32_e32 v64, v0
	v_mov_b32_e32 v65, v0
	v_mov_b32_e32 v66, v0
	v_mov_b32_e32 v67, v0
	v_mov_b32_e32 v68, v0
	v_mov_b32_e32 v69, v0
	v_mov_b32_e32 v70, v0
	v_mov_b32_e32 v71, v0
	v_mov_b32_e32 v80, v0
	v_mov_b32_e32 v81, v0
	v_mov_b32_e32 v82, v0
	v_mov_b32_e32 v83, v0
	v_mov_b32_e32 v84, v0
	v_mov_b32_e32 v85, v0
	v_mov_b32_e32 v86, v0
	v_mov_b32_e32 v87, v0
	v_mov_b32_e32 v96, v0
	v_mov_b32_e32 v97, v0
	v_mov_b32_e32 v98, v0
	v_mov_b32_e32 v99, v0
	v_mov_b32_e32 v100, v0
	v_mov_b32_e32 v101, v0
	v_mov_b32_e32 v102, v0
	v_mov_b32_e32 v103, v0
	v_mov_b32_e32 v112, v0
	v_mov_b32_e32 v113, v0
	v_mov_b32_e32 v114, v0
	v_mov_b32_e32 v115, v0
	v_mov_b32_e32 v116, v0
	v_mov_b32_e32 v117, v0
	v_mov_b32_e32 v118, v0
	v_mov_b32_e32 v119, v0
	v_mov_b32_e32 v72, v0
	v_mov_b32_e32 v73, v0
	v_mov_b32_e32 v74, v0
	v_mov_b32_e32 v75, v0
	v_mov_b32_e32 v76, v0
	v_mov_b32_e32 v77, v0
	v_mov_b32_e32 v78, v0
	v_mov_b32_e32 v79, v0
	v_mov_b32_e32 v88, v0
	v_mov_b32_e32 v89, v0
	v_mov_b32_e32 v90, v0
	v_mov_b32_e32 v91, v0
	v_mov_b32_e32 v92, v0
	v_mov_b32_e32 v93, v0
	v_mov_b32_e32 v94, v0
	v_mov_b32_e32 v95, v0
	v_mov_b32_e32 v104, v0
	v_mov_b32_e32 v105, v0
	v_mov_b32_e32 v106, v0
	v_mov_b32_e32 v107, v0
	v_mov_b32_e32 v108, v0
	v_mov_b32_e32 v109, v0
	v_mov_b32_e32 v110, v0
	v_mov_b32_e32 v111, v0
	v_mov_b32_e32 v120, v0
	v_mov_b32_e32 v121, v0
	v_mov_b32_e32 v122, v0
	v_mov_b32_e32 v123, v0
	v_mov_b32_e32 v124, v0
	v_mov_b32_e32 v125, v0
	v_mov_b32_e32 v126, v0
	v_mov_b32_e32 v127, v0
	.p2align 6

.LBB0_483:
	s_add_u32 s43, s22, 0x100
	v_mov_b32_e32 v0, 0
	s_addc_u32 s44, s23, 0
	s_mov_b32 s45, -2
	v_mov_b32_e32 v1, v0
	v_mov_b32_e32 v2, v0
	v_mov_b32_e32 v3, v0
	v_mov_b32_e32 v4, v0
	v_mov_b32_e32 v5, v0
	v_mov_b32_e32 v6, v0
	v_mov_b32_e32 v7, v0
	v_mov_b32_e32 v16, v0
	v_mov_b32_e32 v17, v0
	v_mov_b32_e32 v18, v0
	v_mov_b32_e32 v19, v0
	v_mov_b32_e32 v20, v0
	v_mov_b32_e32 v21, v0
	v_mov_b32_e32 v22, v0
	v_mov_b32_e32 v23, v0
	v_mov_b32_e32 v32, v0
	v_mov_b32_e32 v33, v0
	v_mov_b32_e32 v34, v0
	v_mov_b32_e32 v35, v0
	v_mov_b32_e32 v36, v0
	v_mov_b32_e32 v37, v0
	v_mov_b32_e32 v38, v0
	v_mov_b32_e32 v39, v0
	v_mov_b32_e32 v48, v0
	v_mov_b32_e32 v49, v0
	v_mov_b32_e32 v50, v0
	v_mov_b32_e32 v51, v0
	v_mov_b32_e32 v52, v0
	v_mov_b32_e32 v53, v0
	v_mov_b32_e32 v54, v0
	v_mov_b32_e32 v55, v0
	v_mov_b32_e32 v8, v0
	v_mov_b32_e32 v9, v0
	v_mov_b32_e32 v10, v0
	v_mov_b32_e32 v11, v0
	v_mov_b32_e32 v12, v0
	v_mov_b32_e32 v13, v0
	v_mov_b32_e32 v14, v0
	v_mov_b32_e32 v15, v0
	v_mov_b32_e32 v24, v0
	v_mov_b32_e32 v25, v0
	v_mov_b32_e32 v26, v0
	v_mov_b32_e32 v27, v0
	v_mov_b32_e32 v28, v0
	v_mov_b32_e32 v29, v0
	v_mov_b32_e32 v30, v0
	v_mov_b32_e32 v31, v0
	v_mov_b32_e32 v40, v0
	v_mov_b32_e32 v41, v0
	v_mov_b32_e32 v42, v0
	v_mov_b32_e32 v43, v0
	v_mov_b32_e32 v44, v0
	v_mov_b32_e32 v45, v0
	v_mov_b32_e32 v46, v0
	v_mov_b32_e32 v47, v0
	v_mov_b32_e32 v56, v0
	v_mov_b32_e32 v57, v0
	v_mov_b32_e32 v58, v0
	v_mov_b32_e32 v59, v0
	v_mov_b32_e32 v60, v0
	v_mov_b32_e32 v61, v0
	v_mov_b32_e32 v62, v0
	v_mov_b32_e32 v63, v0
	v_mov_b32_e32 v64, v0
	v_mov_b32_e32 v65, v0
	v_mov_b32_e32 v66, v0
	v_mov_b32_e32 v67, v0
	v_mov_b32_e32 v68, v0
	v_mov_b32_e32 v69, v0
	v_mov_b32_e32 v70, v0
	v_mov_b32_e32 v71, v0
	v_mov_b32_e32 v80, v0
	v_mov_b32_e32 v81, v0
	v_mov_b32_e32 v82, v0
	v_mov_b32_e32 v83, v0
	v_mov_b32_e32 v84, v0
	v_mov_b32_e32 v85, v0
	v_mov_b32_e32 v86, v0
	v_mov_b32_e32 v87, v0
	v_mov_b32_e32 v96, v0
	v_mov_b32_e32 v97, v0
	v_mov_b32_e32 v98, v0
	v_mov_b32_e32 v99, v0
	v_mov_b32_e32 v100, v0
	v_mov_b32_e32 v101, v0
	v_mov_b32_e32 v102, v0
	v_mov_b32_e32 v103, v0
	v_mov_b32_e32 v112, v0
	v_mov_b32_e32 v113, v0
	v_mov_b32_e32 v114, v0
	v_mov_b32_e32 v115, v0
	v_mov_b32_e32 v116, v0
	v_mov_b32_e32 v117, v0
	v_mov_b32_e32 v118, v0
	v_mov_b32_e32 v119, v0
	v_mov_b32_e32 v72, v0
	v_mov_b32_e32 v73, v0
	v_mov_b32_e32 v74, v0
	v_mov_b32_e32 v75, v0
	v_mov_b32_e32 v76, v0
	v_mov_b32_e32 v77, v0
	v_mov_b32_e32 v78, v0
	v_mov_b32_e32 v79, v0
	v_mov_b32_e32 v88, v0
	v_mov_b32_e32 v89, v0
	v_mov_b32_e32 v90, v0
	v_mov_b32_e32 v91, v0
	v_mov_b32_e32 v92, v0
	v_mov_b32_e32 v93, v0
	v_mov_b32_e32 v94, v0
	v_mov_b32_e32 v95, v0
	v_mov_b32_e32 v104, v0
	v_mov_b32_e32 v105, v0
	v_mov_b32_e32 v106, v0
	v_mov_b32_e32 v107, v0
	v_mov_b32_e32 v108, v0
	v_mov_b32_e32 v109, v0
	v_mov_b32_e32 v110, v0
	v_mov_b32_e32 v111, v0
	v_mov_b32_e32 v120, v0
	v_mov_b32_e32 v121, v0
	v_mov_b32_e32 v122, v0
	v_mov_b32_e32 v123, v0
	v_mov_b32_e32 v124, v0
	v_mov_b32_e32 v125, v0
	v_mov_b32_e32 v126, v0
	v_mov_b32_e32 v127, v0
	.p2align 6
